# lever 7: fused-norm epilogue row-sum butterflies (xor 16 / xor 32) done with v_permlane16_swap / v_permlane32_swap instead of ds_bpermute_b32 LDS round trips (64 sites, bit-identical sums)
# speedup vs baseline: 1.0018x; 1.0018x over previous
.LBB0_345:
	s_lshl_b32 s35, s0, 8
	s_add_i32 s1, s35, 0xfffff000
	v_lshl_add_u32 v178, s68, 8, v196
	v_add_u32_e32 v170, s35, v194
	s_lshr_b32 s1, s1, 11
	v_ashrrev_i32_e32 v179, 31, v178
	v_ashrrev_i32_e32 v171, 31, v170
	s_mulk_i32 s1, 0x1800
	s_cmp_gt_i32 s0, 15
	v_lshl_add_u64 v[172:173], v[178:179], 1, s[20:21]
	v_lshlrev_b64 v[168:169], 11, v[170:171]
	s_cselect_b32 s18, s1, 0x6000
	v_lshl_add_u64 v[112:113], v[172:173], 0, v[168:169]
	s_lshl_b64 s[70:71], s[18:19], 2
	global_load_dwordx4 v[174:177], v[112:113], off
	global_load_dwordx4 v[182:185], v[112:113], off offset:256
	s_add_u32 s72, s33, s70
	s_addc_u32 s73, s76, s71
	v_lshl_add_u64 v[112:113], v[178:179], 2, s[72:73]
	global_load_dwordx4 v[132:135], v[112:113], off
	global_load_dwordx4 v[128:131], v[112:113], off offset:16
	global_load_dwordx4 v[120:123], v[112:113], off offset:512
	s_nop 0
	global_load_dwordx4 v[112:115], v[112:113], off offset:528
	v_or_b32_e32 v144, 16, v170
	v_ashrrev_i32_e32 v145, 31, v144
	v_lshlrev_b64 v[180:181], 11, v[144:145]
	v_lshl_add_u64 v[144:145], v[172:173], 0, v[180:181]
	global_load_dwordx4 v[148:151], v[144:145], off
	s_nop 0
	global_load_dwordx4 v[144:147], v[144:145], off offset:256
	v_and_b32_e32 v187, 64, v217
	v_xor_b32_e32 v186, 16, v217
	v_add_u32_e32 v223, 64, v187
	v_cmp_lt_i32_e32 vcc, v186, v223
	s_waitcnt vmcnt(0)
	v_and_b32_e32 v187, 0xffff0000, v174
	v_cndmask_b32_e32 v186, v217, v186, vcc
	v_lshlrev_b32_e32 v222, 2, v186
	v_lshlrev_b32_e32 v186, 16, v174
	v_lshlrev_b32_e32 v174, 16, v175
	v_and_b32_e32 v175, 0xffff0000, v175
	v_lshlrev_b32_e32 v188, 16, v176
	v_and_b32_e32 v189, 0xffff0000, v176
	v_lshlrev_b32_e32 v176, 16, v177
	v_and_b32_e32 v177, 0xffff0000, v177
	v_lshlrev_b32_e32 v190, 16, v182
	v_and_b32_e32 v191, 0xffff0000, v182
	v_lshlrev_b32_e32 v182, 16, v183
	v_and_b32_e32 v183, 0xffff0000, v183
	v_pk_fma_f32 v[142:143], v[142:143], v[134:135], v[174:175]
	v_pk_fma_f32 v[140:141], v[140:141], v[132:133], v[186:187]
	v_pk_fma_f32 v[138:139], v[138:139], v[130:131], v[176:177]
	v_pk_fma_f32 v[136:137], v[136:137], v[128:129], v[188:189]
	v_lshlrev_b32_e32 v192, 16, v184
	v_and_b32_e32 v193, 0xffff0000, v184
	v_lshlrev_b32_e32 v184, 16, v185
	v_and_b32_e32 v185, 0xffff0000, v185
	v_pk_fma_f32 v[126:127], v[126:127], v[122:123], v[182:183]
	v_pk_fma_f32 v[124:125], v[124:125], v[120:121], v[190:191]
	v_mul_f32_e32 v174, v141, v141
	v_mul_f32_e32 v175, v143, v143
	v_mul_f32_e32 v176, v137, v137
	v_mul_f32_e32 v177, v139, v139
	v_pk_fma_f32 v[118:119], v[118:119], v[114:115], v[184:185]
	v_pk_fma_f32 v[116:117], v[116:117], v[112:113], v[192:193]
	v_mul_f32_e32 v182, v125, v125
	v_mul_f32_e32 v183, v127, v127
	v_fmac_f32_e32 v174, v140, v140
	v_fmac_f32_e32 v175, v142, v142
	v_fmac_f32_e32 v176, v136, v136
	v_fmac_f32_e32 v177, v138, v138
	v_mul_f32_e32 v184, v117, v117
	v_mul_f32_e32 v185, v119, v119
	v_fmac_f32_e32 v182, v124, v124
	v_fmac_f32_e32 v183, v126, v126
	v_add_f32_e32 v174, v174, v175
	v_add_f32_e32 v175, v176, v177
	v_fmac_f32_e32 v184, v116, v116
	v_fmac_f32_e32 v185, v118, v118
	v_add_f32_e32 v176, v182, v183
	v_add_f32_e32 v174, v174, v175
	v_add_f32_e32 v174, v174, v176
	v_add_f32_e32 v175, v184, v185
	v_add_f32_e32 v174, v175, v174
	v_mov_b32_e32 v175, v174
	s_nop 1
	v_permlane16_swap_b32_e32 v174, v175
	s_nop 1
	v_xor_b32_e32 v176, 32, v217
	v_cmp_lt_i32_e32 vcc, v176, v223
	s_waitcnt lgkmcnt(0)
	v_add_f32_e32 v174, v174, v175
	v_cndmask_b32_e32 v176, v217, v176, vcc
	v_lshlrev_b32_e32 v223, 2, v176
	v_mov_b32_e32 v175, v174
	s_nop 1
	v_permlane32_swap_b32_e32 v174, v175
	s_nop 1
	s_and_saveexec_b64 s[72:73], s[4:5]
	s_cbranch_execz .LBB0_347
	s_waitcnt lgkmcnt(0)
	v_add_f32_e32 v174, v174, v175
	ds_write_b32 v221, v174
.LBB0_347:
	s_or_b64 exec, exec, s[72:73]
	v_lshlrev_b32_e32 v174, 16, v148
	s_waitcnt lgkmcnt(0)
	v_and_b32_e32 v175, 0xffff0000, v148
	v_lshlrev_b32_e32 v148, 16, v149
	v_and_b32_e32 v149, 0xffff0000, v149
	v_lshlrev_b32_e32 v176, 16, v150
	v_and_b32_e32 v177, 0xffff0000, v150
	v_lshlrev_b32_e32 v150, 16, v151
	v_and_b32_e32 v151, 0xffff0000, v151
	v_lshlrev_b32_e32 v182, 16, v144
	v_and_b32_e32 v183, 0xffff0000, v144
	v_lshlrev_b32_e32 v184, 16, v145
	v_and_b32_e32 v185, 0xffff0000, v145
	v_lshlrev_b32_e32 v186, 16, v146
	v_and_b32_e32 v187, 0xffff0000, v146
	v_lshlrev_b32_e32 v188, 16, v147
	v_and_b32_e32 v189, 0xffff0000, v147
	v_pk_fma_f32 v[144:145], v[110:111], v[134:135], v[148:149]
	v_pk_fma_f32 v[146:147], v[108:109], v[132:133], v[174:175]
	v_pk_fma_f32 v[148:149], v[106:107], v[130:131], v[150:151]
	v_pk_fma_f32 v[150:151], v[104:105], v[128:129], v[176:177]
	v_mul_f32_e32 v108, v147, v147
	v_mul_f32_e32 v109, v145, v145
	v_mul_f32_e32 v104, v151, v151
	v_mul_f32_e32 v105, v149, v149
	v_fmac_f32_e32 v108, v146, v146
	v_fmac_f32_e32 v109, v144, v144
	v_fmac_f32_e32 v104, v150, v150
	v_fmac_f32_e32 v105, v148, v148
	v_add_f32_e32 v108, v108, v109
	v_add_f32_e32 v104, v104, v105
	v_add_f32_e32 v108, v108, v104
	v_pk_fma_f32 v[104:105], v[102:103], v[122:123], v[184:185]
	v_pk_fma_f32 v[106:107], v[100:101], v[120:121], v[182:183]
	v_mul_f32_e32 v101, v105, v105
	v_mul_f32_e32 v100, v107, v107
	v_fmac_f32_e32 v100, v106, v106
	v_fmac_f32_e32 v101, v104, v104
	v_add_f32_e32 v100, v100, v101
	v_add_f32_e32 v100, v108, v100
	v_pk_fma_f32 v[108:109], v[98:99], v[114:115], v[188:189]
	v_pk_fma_f32 v[110:111], v[96:97], v[112:113], v[186:187]
	v_mul_f32_e32 v97, v109, v109
	v_mul_f32_e32 v96, v111, v111
	v_fmac_f32_e32 v96, v110, v110
	v_fmac_f32_e32 v97, v108, v108
	v_add_f32_e32 v96, v96, v97
	v_add_f32_e32 v96, v96, v100
	v_mov_b32_e32 v97, v96
	s_nop 1
	v_permlane16_swap_b32_e32 v96, v97
	s_nop 1
	s_waitcnt lgkmcnt(0)
	v_add_f32_e32 v96, v96, v97
	v_mov_b32_e32 v97, v96
	s_nop 1
	v_permlane32_swap_b32_e32 v96, v97
	s_nop 1
	s_and_saveexec_b64 s[72:73], s[4:5]
	s_cbranch_execz .LBB0_349
	s_waitcnt lgkmcnt(0)
	v_add_f32_e32 v96, v96, v97
	ds_write_b32 v221, v96 offset:256
.LBB0_349:
	s_or_b64 exec, exec, s[72:73]
	v_or_b32_e32 v96, 32, v170
	s_waitcnt lgkmcnt(0)
	v_ashrrev_i32_e32 v97, 31, v96
	v_lshlrev_b64 v[184:185], 11, v[96:97]
	v_lshl_add_u64 v[96:97], v[172:173], 0, v[184:185]
	global_load_dwordx4 v[174:177], v[96:97], off
	global_load_dwordx4 v[186:189], v[96:97], off offset:256
	v_or_b32_e32 v96, 48, v170
	v_ashrrev_i32_e32 v97, 31, v96
	v_lshlrev_b64 v[182:183], 11, v[96:97]
	v_lshl_add_u64 v[96:97], v[172:173], 0, v[182:183]
	global_load_dwordx4 v[100:103], v[96:97], off
	s_nop 0
	global_load_dwordx4 v[96:99], v[96:97], off offset:256
	s_waitcnt vmcnt(3)
	v_lshlrev_b32_e32 v190, 16, v174
	v_and_b32_e32 v191, 0xffff0000, v174
	v_lshlrev_b32_e32 v174, 16, v175
	v_and_b32_e32 v175, 0xffff0000, v175
	v_lshlrev_b32_e32 v192, 16, v176
	v_and_b32_e32 v193, 0xffff0000, v176
	v_lshlrev_b32_e32 v176, 16, v177
	v_and_b32_e32 v177, 0xffff0000, v177
	s_waitcnt vmcnt(2)
	v_lshlrev_b32_e32 v224, 16, v186
	v_and_b32_e32 v225, 0xffff0000, v186
	v_lshlrev_b32_e32 v186, 16, v187
	v_and_b32_e32 v187, 0xffff0000, v187
	v_pk_fma_f32 v[94:95], v[94:95], v[134:135], v[174:175]
	v_pk_fma_f32 v[92:93], v[92:93], v[132:133], v[190:191]
	v_pk_fma_f32 v[90:91], v[90:91], v[130:131], v[176:177]
	v_pk_fma_f32 v[88:89], v[88:89], v[128:129], v[192:193]
	v_lshlrev_b32_e32 v226, 16, v188
	v_and_b32_e32 v227, 0xffff0000, v188
	v_lshlrev_b32_e32 v188, 16, v189
	v_and_b32_e32 v189, 0xffff0000, v189
	v_pk_fma_f32 v[86:87], v[86:87], v[122:123], v[186:187]
	v_pk_fma_f32 v[84:85], v[84:85], v[120:121], v[224:225]
	v_mul_f32_e32 v174, v93, v93
	v_mul_f32_e32 v175, v95, v95
	v_mul_f32_e32 v176, v89, v89
	v_mul_f32_e32 v177, v91, v91
	v_pk_fma_f32 v[82:83], v[82:83], v[114:115], v[188:189]
	v_pk_fma_f32 v[80:81], v[80:81], v[112:113], v[226:227]
	v_mul_f32_e32 v186, v85, v85
	v_mul_f32_e32 v187, v87, v87
	v_fmac_f32_e32 v174, v92, v92
	v_fmac_f32_e32 v175, v94, v94
	v_fmac_f32_e32 v176, v88, v88
	v_fmac_f32_e32 v177, v90, v90
	v_mul_f32_e32 v188, v81, v81
	v_mul_f32_e32 v189, v83, v83
	v_fmac_f32_e32 v186, v84, v84
	v_fmac_f32_e32 v187, v86, v86
	v_add_f32_e32 v174, v174, v175
	v_add_f32_e32 v175, v176, v177
	v_fmac_f32_e32 v188, v80, v80
	v_fmac_f32_e32 v189, v82, v82
	v_add_f32_e32 v176, v186, v187
	v_add_f32_e32 v174, v174, v175
	v_add_f32_e32 v174, v174, v176
	v_add_f32_e32 v175, v188, v189
	v_add_f32_e32 v174, v175, v174
	v_mov_b32_e32 v175, v174
	s_nop 1
	v_permlane16_swap_b32_e32 v174, v175
	s_nop 1
	s_waitcnt lgkmcnt(0)
	v_add_f32_e32 v174, v174, v175
	v_mov_b32_e32 v175, v174
	s_nop 1
	v_permlane32_swap_b32_e32 v174, v175
	s_nop 1
	s_and_saveexec_b64 s[72:73], s[4:5]
	s_cbranch_execz .LBB0_351
	s_waitcnt lgkmcnt(0)
	v_add_f32_e32 v174, v174, v175
	ds_write_b32 v221, v174 offset:512
.LBB0_351:
	s_or_b64 exec, exec, s[72:73]
	s_waitcnt vmcnt(1)
	v_lshlrev_b32_e32 v174, 16, v100
	s_waitcnt lgkmcnt(0)
	v_and_b32_e32 v175, 0xffff0000, v100
	v_lshlrev_b32_e32 v100, 16, v101
	v_and_b32_e32 v101, 0xffff0000, v101
	v_lshlrev_b32_e32 v176, 16, v102
	v_and_b32_e32 v177, 0xffff0000, v102
	v_lshlrev_b32_e32 v186, 16, v103
	v_and_b32_e32 v187, 0xffff0000, v103
	v_pk_fma_f32 v[100:101], v[78:79], v[134:135], v[100:101]
	v_pk_fma_f32 v[102:103], v[76:77], v[132:133], v[174:175]
	v_pk_fma_f32 v[174:175], v[74:75], v[130:131], v[186:187]
	v_pk_fma_f32 v[176:177], v[72:73], v[128:129], v[176:177]
	v_mul_f32_e32 v76, v103, v103
	v_mul_f32_e32 v77, v101, v101
	v_mul_f32_e32 v72, v177, v177
	v_mul_f32_e32 v73, v175, v175
	v_fmac_f32_e32 v76, v102, v102
	v_fmac_f32_e32 v77, v100, v100
	v_fmac_f32_e32 v72, v176, v176
	v_fmac_f32_e32 v73, v174, v174
	s_waitcnt vmcnt(0)
	v_lshlrev_b32_e32 v188, 16, v96
	v_and_b32_e32 v189, 0xffff0000, v96
	v_lshlrev_b32_e32 v96, 16, v97
	v_and_b32_e32 v97, 0xffff0000, v97
	v_add_f32_e32 v76, v76, v77
	v_add_f32_e32 v72, v72, v73
	v_add_f32_e32 v76, v76, v72
	v_pk_fma_f32 v[72:73], v[70:71], v[122:123], v[96:97]
	v_pk_fma_f32 v[74:75], v[68:69], v[120:121], v[188:189]
	v_mul_f32_e32 v69, v73, v73
	v_mul_f32_e32 v68, v75, v75
	v_fmac_f32_e32 v68, v74, v74
	v_fmac_f32_e32 v69, v72, v72
	v_lshlrev_b32_e32 v190, 16, v98
	v_and_b32_e32 v191, 0xffff0000, v98
	v_lshlrev_b32_e32 v98, 16, v99
	v_and_b32_e32 v99, 0xffff0000, v99
	v_add_f32_e32 v68, v68, v69
	v_add_f32_e32 v68, v76, v68
	v_pk_fma_f32 v[76:77], v[66:67], v[114:115], v[98:99]
	v_pk_fma_f32 v[78:79], v[64:65], v[112:113], v[190:191]
	v_mul_f32_e32 v65, v77, v77
	v_mul_f32_e32 v64, v79, v79
	v_fmac_f32_e32 v64, v78, v78
	v_fmac_f32_e32 v65, v76, v76
	v_add_f32_e32 v64, v64, v65
	v_add_f32_e32 v64, v64, v68
	v_mov_b32_e32 v65, v64
	s_nop 1
	v_permlane16_swap_b32_e32 v64, v65
	s_nop 1
	s_waitcnt lgkmcnt(0)
	v_add_f32_e32 v64, v64, v65
	v_mov_b32_e32 v65, v64
	s_nop 1
	v_permlane32_swap_b32_e32 v64, v65
	s_nop 1
	s_and_saveexec_b64 s[72:73], s[4:5]
	s_cbranch_execz .LBB0_353
	s_waitcnt lgkmcnt(0)
	v_add_f32_e32 v64, v64, v65
	ds_write_b32 v221, v64 offset:768
.LBB0_353:
	s_or_b64 exec, exec, s[72:73]
	s_waitcnt lgkmcnt(0)
	v_lshlrev_b64 v[64:65], 11, v[170:171]
	s_mov_b64 s[72:73], 0x40000
	v_lshl_add_u64 v[188:189], v[64:65], 0, s[72:73]
	v_lshl_add_u64 v[66:67], v[172:173], 0, v[188:189]
	global_load_dwordx4 v[96:99], v[66:67], off
	global_load_dwordx4 v[190:193], v[66:67], off offset:256
	s_mov_b64 s[72:73], 0x48000
	v_lshl_add_u64 v[186:187], v[64:65], 0, s[72:73]
	v_lshl_add_u64 v[64:65], v[172:173], 0, v[186:187]
	global_load_dwordx4 v[68:71], v[64:65], off
	s_nop 0
	global_load_dwordx4 v[64:67], v[64:65], off offset:256
	s_waitcnt vmcnt(3)
	v_lshlrev_b32_e32 v224, 16, v96
	v_and_b32_e32 v225, 0xffff0000, v96
	v_lshlrev_b32_e32 v96, 16, v97
	v_and_b32_e32 v97, 0xffff0000, v97
	v_lshlrev_b32_e32 v226, 16, v98
	v_and_b32_e32 v227, 0xffff0000, v98
	v_lshlrev_b32_e32 v98, 16, v99
	v_and_b32_e32 v99, 0xffff0000, v99
	s_waitcnt vmcnt(2)
	v_lshlrev_b32_e32 v228, 16, v190
	v_and_b32_e32 v229, 0xffff0000, v190
	v_lshlrev_b32_e32 v190, 16, v191
	v_and_b32_e32 v191, 0xffff0000, v191
	v_pk_fma_f32 v[62:63], v[62:63], v[134:135], v[96:97]
	v_pk_fma_f32 v[60:61], v[60:61], v[132:133], v[224:225]
	v_pk_fma_f32 v[58:59], v[58:59], v[130:131], v[98:99]
	v_pk_fma_f32 v[56:57], v[56:57], v[128:129], v[226:227]
	v_lshlrev_b32_e32 v230, 16, v192
	v_and_b32_e32 v231, 0xffff0000, v192
	v_lshlrev_b32_e32 v192, 16, v193
	v_and_b32_e32 v193, 0xffff0000, v193
	v_pk_fma_f32 v[54:55], v[54:55], v[122:123], v[190:191]
	v_pk_fma_f32 v[52:53], v[52:53], v[120:121], v[228:229]
	v_mul_f32_e32 v96, v61, v61
	v_mul_f32_e32 v97, v63, v63
	v_mul_f32_e32 v98, v57, v57
	v_mul_f32_e32 v99, v59, v59
	v_pk_fma_f32 v[50:51], v[50:51], v[114:115], v[192:193]
	v_pk_fma_f32 v[48:49], v[48:49], v[112:113], v[230:231]
	v_mul_f32_e32 v190, v53, v53
	v_mul_f32_e32 v191, v55, v55
	v_fmac_f32_e32 v96, v60, v60
	v_fmac_f32_e32 v97, v62, v62
	v_fmac_f32_e32 v98, v56, v56
	v_fmac_f32_e32 v99, v58, v58
	v_mul_f32_e32 v192, v49, v49
	v_mul_f32_e32 v193, v51, v51
	v_fmac_f32_e32 v190, v52, v52
	v_fmac_f32_e32 v191, v54, v54
	v_add_f32_e32 v96, v96, v97
	v_add_f32_e32 v97, v98, v99
	v_fmac_f32_e32 v192, v48, v48
	v_fmac_f32_e32 v193, v50, v50
	v_add_f32_e32 v98, v190, v191
	v_add_f32_e32 v96, v96, v97
	v_add_f32_e32 v96, v96, v98
	v_add_f32_e32 v97, v192, v193
	v_add_f32_e32 v96, v97, v96
	v_mov_b32_e32 v97, v96
	s_nop 1
	v_permlane16_swap_b32_e32 v96, v97
	s_nop 1
	s_waitcnt lgkmcnt(0)
	v_add_f32_e32 v96, v96, v97
	v_mov_b32_e32 v97, v96
	s_nop 1
	v_permlane32_swap_b32_e32 v96, v97
	s_nop 1
	s_and_saveexec_b64 s[72:73], s[4:5]
	s_cbranch_execz .LBB0_355
	s_waitcnt lgkmcnt(0)
	v_add_f32_e32 v96, v96, v97
	ds_write_b32 v221, v96 offset:2048
.LBB0_355:
	s_or_b64 exec, exec, s[72:73]
	s_waitcnt vmcnt(1)
	v_lshlrev_b32_e32 v96, 16, v68
	s_waitcnt lgkmcnt(0)
	v_and_b32_e32 v97, 0xffff0000, v68
	v_lshlrev_b32_e32 v68, 16, v69
	v_and_b32_e32 v69, 0xffff0000, v69
	v_lshlrev_b32_e32 v98, 16, v70
	v_and_b32_e32 v99, 0xffff0000, v70
	v_lshlrev_b32_e32 v70, 16, v71
	v_and_b32_e32 v71, 0xffff0000, v71
	s_waitcnt vmcnt(0)
	v_lshlrev_b32_e32 v190, 16, v64
	v_and_b32_e32 v191, 0xffff0000, v64
	v_lshlrev_b32_e32 v192, 16, v65
	v_and_b32_e32 v193, 0xffff0000, v65
	v_lshlrev_b32_e32 v224, 16, v66
	v_and_b32_e32 v225, 0xffff0000, v66
	v_lshlrev_b32_e32 v226, 16, v67
	v_and_b32_e32 v227, 0xffff0000, v67
	v_pk_fma_f32 v[64:65], v[46:47], v[134:135], v[68:69]
	v_pk_fma_f32 v[66:67], v[44:45], v[132:133], v[96:97]
	v_pk_fma_f32 v[68:69], v[42:43], v[130:131], v[70:71]
	v_pk_fma_f32 v[70:71], v[40:41], v[128:129], v[98:99]
	v_mul_f32_e32 v44, v67, v67
	v_mul_f32_e32 v45, v65, v65
	v_mul_f32_e32 v40, v71, v71
	v_mul_f32_e32 v41, v69, v69
	v_fmac_f32_e32 v44, v66, v66
	v_fmac_f32_e32 v45, v64, v64
	v_fmac_f32_e32 v40, v70, v70
	v_fmac_f32_e32 v41, v68, v68
	v_add_f32_e32 v44, v44, v45
	v_add_f32_e32 v40, v40, v41
	v_add_f32_e32 v44, v44, v40
	v_pk_fma_f32 v[40:41], v[38:39], v[122:123], v[192:193]
	v_pk_fma_f32 v[42:43], v[36:37], v[120:121], v[190:191]
	v_mul_f32_e32 v37, v41, v41
	v_mul_f32_e32 v36, v43, v43
	v_fmac_f32_e32 v36, v42, v42
	v_fmac_f32_e32 v37, v40, v40
	v_add_f32_e32 v36, v36, v37
	v_add_f32_e32 v36, v44, v36
	v_pk_fma_f32 v[44:45], v[34:35], v[114:115], v[226:227]
	v_pk_fma_f32 v[46:47], v[32:33], v[112:113], v[224:225]
	v_mul_f32_e32 v33, v45, v45
	v_mul_f32_e32 v32, v47, v47
	v_fmac_f32_e32 v32, v46, v46
	v_fmac_f32_e32 v33, v44, v44
	v_add_f32_e32 v32, v32, v33
	v_add_f32_e32 v32, v32, v36
	v_mov_b32_e32 v33, v32
	s_nop 1
	v_permlane16_swap_b32_e32 v32, v33
	s_nop 1
	s_waitcnt lgkmcnt(0)
	v_add_f32_e32 v32, v32, v33
	v_mov_b32_e32 v33, v32
	s_nop 1
	v_permlane32_swap_b32_e32 v32, v33
	s_nop 1
	s_and_saveexec_b64 s[72:73], s[4:5]
	s_cbranch_execz .LBB0_357
	s_waitcnt lgkmcnt(0)
	v_add_f32_e32 v32, v32, v33
	ds_write_b32 v221, v32 offset:2304
.LBB0_357:
	s_or_b64 exec, exec, s[72:73]
	s_waitcnt lgkmcnt(0)
	v_lshlrev_b64 v[32:33], 11, v[170:171]
	s_mov_b64 s[72:73], 0x50000
	v_lshl_add_u64 v[192:193], v[32:33], 0, s[72:73]
	v_lshl_add_u64 v[34:35], v[172:173], 0, v[192:193]
	global_load_dwordx4 v[96:99], v[34:35], off
	global_load_dwordx4 v[224:227], v[34:35], off offset:256
	s_mov_b64 s[72:73], 0x58000
	v_lshl_add_u64 v[190:191], v[32:33], 0, s[72:73]
	v_lshl_add_u64 v[32:33], v[172:173], 0, v[190:191]
	global_load_dwordx4 v[36:39], v[32:33], off
	s_nop 0
	global_load_dwordx4 v[32:35], v[32:33], off offset:256
	s_waitcnt vmcnt(3)
	v_lshlrev_b32_e32 v170, 16, v96
	v_and_b32_e32 v171, 0xffff0000, v96
	v_lshlrev_b32_e32 v96, 16, v97
	v_and_b32_e32 v97, 0xffff0000, v97
	v_lshlrev_b32_e32 v172, 16, v98
	v_and_b32_e32 v173, 0xffff0000, v98
	v_lshlrev_b32_e32 v228, 16, v99
	v_and_b32_e32 v229, 0xffff0000, v99
	s_waitcnt vmcnt(2)
	v_lshlrev_b32_e32 v230, 16, v224
	v_and_b32_e32 v231, 0xffff0000, v224
	v_lshlrev_b32_e32 v224, 16, v225
	v_and_b32_e32 v225, 0xffff0000, v225
	v_lshlrev_b32_e32 v232, 16, v226
	v_and_b32_e32 v233, 0xffff0000, v226
	v_lshlrev_b32_e32 v226, 16, v227
	v_and_b32_e32 v227, 0xffff0000, v227
	v_pk_fma_f32 v[96:97], v[30:31], v[134:135], v[96:97]
	v_pk_fma_f32 v[98:99], v[28:29], v[132:133], v[170:171]
	v_pk_fma_f32 v[170:171], v[26:27], v[130:131], v[228:229]
	v_pk_fma_f32 v[172:173], v[24:25], v[128:129], v[172:173]
	v_pk_fma_f32 v[24:25], v[22:23], v[122:123], v[224:225]
	v_pk_fma_f32 v[26:27], v[20:21], v[120:121], v[230:231]
	v_pk_fma_f32 v[28:29], v[18:19], v[114:115], v[226:227]
	v_pk_fma_f32 v[30:31], v[16:17], v[112:113], v[232:233]
	v_mul_f32_e32 v16, v99, v99
	v_mul_f32_e32 v17, v97, v97
	v_mul_f32_e32 v18, v173, v173
	v_mul_f32_e32 v19, v171, v171
	v_mul_f32_e32 v20, v27, v27
	v_mul_f32_e32 v21, v25, v25
	v_fmac_f32_e32 v16, v98, v98
	v_fmac_f32_e32 v17, v96, v96
	v_fmac_f32_e32 v18, v172, v172
	v_fmac_f32_e32 v19, v170, v170
	v_mul_f32_e32 v22, v31, v31
	v_mul_f32_e32 v23, v29, v29
	v_fmac_f32_e32 v20, v26, v26
	v_fmac_f32_e32 v21, v24, v24
	v_add_f32_e32 v16, v16, v17
	v_add_f32_e32 v17, v18, v19
	v_fmac_f32_e32 v22, v30, v30
	v_fmac_f32_e32 v23, v28, v28
	v_add_f32_e32 v18, v20, v21
	v_add_f32_e32 v16, v16, v17
	v_add_f32_e32 v16, v16, v18
	v_add_f32_e32 v17, v22, v23
	v_add_f32_e32 v16, v17, v16
	v_mov_b32_e32 v17, v16
	s_nop 1
	v_permlane16_swap_b32_e32 v16, v17
	s_nop 1
	s_waitcnt lgkmcnt(0)
	v_add_f32_e32 v16, v16, v17
	v_mov_b32_e32 v17, v16
	s_nop 1
	v_permlane32_swap_b32_e32 v16, v17
	s_nop 1
	s_and_saveexec_b64 s[72:73], s[4:5]
	s_cbranch_execz .LBB0_359
	s_waitcnt lgkmcnt(0)
	v_add_f32_e32 v16, v16, v17
	ds_write_b32 v221, v16 offset:2560
.LBB0_359:
	s_or_b64 exec, exec, s[72:73]
	s_waitcnt vmcnt(1)
	v_lshlrev_b32_e32 v16, 16, v36
	s_waitcnt lgkmcnt(0)
	v_and_b32_e32 v17, 0xffff0000, v36
	v_lshlrev_b32_e32 v18, 16, v37
	v_and_b32_e32 v19, 0xffff0000, v37
	v_lshlrev_b32_e32 v20, 16, v38
	v_and_b32_e32 v21, 0xffff0000, v38
	v_lshlrev_b32_e32 v22, 16, v39
	v_and_b32_e32 v23, 0xffff0000, v39
	s_waitcnt vmcnt(0)
	v_lshlrev_b32_e32 v36, 16, v32
	v_and_b32_e32 v37, 0xffff0000, v32
	v_lshlrev_b32_e32 v32, 16, v33
	v_and_b32_e32 v33, 0xffff0000, v33
	v_pk_fma_f32 v[134:135], v[14:15], v[134:135], v[18:19]
	v_pk_fma_f32 v[132:133], v[12:13], v[132:133], v[16:17]
	v_pk_fma_f32 v[130:131], v[10:11], v[130:131], v[22:23]
	v_pk_fma_f32 v[128:129], v[8:9], v[128:129], v[20:21]
	v_lshlrev_b32_e32 v38, 16, v34
	v_and_b32_e32 v39, 0xffff0000, v34
	v_lshlrev_b32_e32 v224, 16, v35
	v_and_b32_e32 v225, 0xffff0000, v35
	v_mul_f32_e32 v12, v133, v133
	v_mul_f32_e32 v13, v135, v135
	v_mul_f32_e32 v8, v129, v129
	v_mul_f32_e32 v9, v131, v131
	v_pk_fma_f32 v[32:33], v[6:7], v[122:123], v[32:33]
	v_pk_fma_f32 v[34:35], v[4:5], v[120:121], v[36:37]
	v_fmac_f32_e32 v12, v132, v132
	v_fmac_f32_e32 v13, v134, v134
	v_fmac_f32_e32 v8, v128, v128
	v_fmac_f32_e32 v9, v130, v130
	v_mul_f32_e32 v4, v35, v35
	v_mul_f32_e32 v5, v33, v33
	v_pk_fma_f32 v[36:37], v[2:3], v[114:115], v[224:225]
	v_pk_fma_f32 v[38:39], v[0:1], v[112:113], v[38:39]
	v_add_f32_e32 v12, v12, v13
	v_add_f32_e32 v8, v8, v9
	v_fmac_f32_e32 v4, v34, v34
	v_fmac_f32_e32 v5, v32, v32
	v_mul_f32_e32 v0, v39, v39
	v_mul_f32_e32 v1, v37, v37
	v_add_f32_e32 v8, v12, v8
	v_add_f32_e32 v4, v4, v5
	v_fmac_f32_e32 v0, v38, v38
	v_fmac_f32_e32 v1, v36, v36
	v_add_f32_e32 v4, v8, v4
	v_add_f32_e32 v0, v0, v1
	v_add_f32_e32 v0, v0, v4
	v_mov_b32_e32 v1, v0
	s_nop 1
	v_permlane16_swap_b32_e32 v0, v1
	s_nop 1
	s_waitcnt lgkmcnt(0)
	v_add_f32_e32 v0, v0, v1
	v_mov_b32_e32 v1, v0
	s_nop 1
	v_permlane32_swap_b32_e32 v0, v1
	s_nop 1
	s_and_saveexec_b64 s[72:73], s[4:5]
	s_cbranch_execz .LBB0_361
	s_waitcnt lgkmcnt(0)
	v_add_f32_e32 v0, v0, v1
	ds_write_b32 v221, v0 offset:2816

.LBB0_508:
	s_lshl_b32 s71, s0, 8
	s_add_i32 s1, s71, 0xfffff000
	v_lshl_add_u32 v170, s78, 8, v196
	v_add_u32_e32 v186, s71, v194
	s_lshr_b32 s1, s1, 11
	v_ashrrev_i32_e32 v171, 31, v170
	v_ashrrev_i32_e32 v187, 31, v186
	s_mulk_i32 s1, 0x1800
	s_cmp_gt_i32 s0, 15
	v_lshl_add_u64 v[190:191], v[170:171], 1, s[38:39]
	v_lshlrev_b64 v[168:169], 11, v[186:187]
	s_cselect_b32 s28, s1, 0x6000
	v_lshl_add_u64 v[112:113], v[190:191], 0, v[168:169]
	s_lshl_b64 s[80:81], s[28:29], 2
	global_load_dwordx4 v[172:175], v[112:113], off
	global_load_dwordx4 v[176:179], v[112:113], off offset:256
	s_add_u32 s62, s96, s80
	s_addc_u32 s63, s97, s81
	v_lshl_add_u64 v[112:113], v[170:171], 2, s[62:63]
	global_load_dwordx4 v[132:135], v[112:113], off
	global_load_dwordx4 v[128:131], v[112:113], off offset:16
	global_load_dwordx4 v[120:123], v[112:113], off offset:512
	s_nop 0
	global_load_dwordx4 v[112:115], v[112:113], off offset:528
	v_or_b32_e32 v144, 16, v186
	v_ashrrev_i32_e32 v145, 31, v144
	v_lshlrev_b64 v[180:181], 11, v[144:145]
	v_lshl_add_u64 v[144:145], v[190:191], 0, v[180:181]
	global_load_dwordx4 v[148:151], v[144:145], off
	s_nop 0
	global_load_dwordx4 v[144:147], v[144:145], off offset:256
	v_and_b32_e32 v183, 64, v217
	v_xor_b32_e32 v182, 16, v217
	v_add_u32_e32 v223, 64, v183
	v_cmp_lt_i32_e32 vcc, v182, v223
	s_waitcnt vmcnt(0)
	v_and_b32_e32 v183, 0xffff0000, v172
	v_cndmask_b32_e32 v182, v217, v182, vcc
	v_lshlrev_b32_e32 v222, 2, v182
	v_lshlrev_b32_e32 v182, 16, v172
	v_lshlrev_b32_e32 v172, 16, v173
	v_and_b32_e32 v173, 0xffff0000, v173
	v_lshlrev_b32_e32 v184, 16, v174
	v_and_b32_e32 v185, 0xffff0000, v174
	v_lshlrev_b32_e32 v174, 16, v175
	v_and_b32_e32 v175, 0xffff0000, v175
	v_lshlrev_b32_e32 v188, 16, v176
	v_and_b32_e32 v189, 0xffff0000, v176
	v_lshlrev_b32_e32 v176, 16, v177
	v_and_b32_e32 v177, 0xffff0000, v177
	v_pk_fma_f32 v[142:143], v[142:143], v[134:135], v[172:173]
	v_pk_fma_f32 v[140:141], v[140:141], v[132:133], v[182:183]
	v_pk_fma_f32 v[138:139], v[138:139], v[130:131], v[174:175]
	v_pk_fma_f32 v[136:137], v[136:137], v[128:129], v[184:185]
	v_lshlrev_b32_e32 v192, 16, v178
	v_and_b32_e32 v193, 0xffff0000, v178
	v_lshlrev_b32_e32 v178, 16, v179
	v_and_b32_e32 v179, 0xffff0000, v179
	v_pk_fma_f32 v[126:127], v[126:127], v[122:123], v[176:177]
	v_pk_fma_f32 v[124:125], v[124:125], v[120:121], v[188:189]
	v_mul_f32_e32 v172, v141, v141
	v_mul_f32_e32 v173, v143, v143
	v_mul_f32_e32 v174, v137, v137
	v_mul_f32_e32 v175, v139, v139
	v_pk_fma_f32 v[118:119], v[118:119], v[114:115], v[178:179]
	v_pk_fma_f32 v[116:117], v[116:117], v[112:113], v[192:193]
	v_mul_f32_e32 v176, v125, v125
	v_mul_f32_e32 v177, v127, v127
	v_fmac_f32_e32 v172, v140, v140
	v_fmac_f32_e32 v173, v142, v142
	v_fmac_f32_e32 v174, v136, v136
	v_fmac_f32_e32 v175, v138, v138
	v_mul_f32_e32 v178, v117, v117
	v_mul_f32_e32 v179, v119, v119
	v_fmac_f32_e32 v176, v124, v124
	v_fmac_f32_e32 v177, v126, v126
	v_add_f32_e32 v172, v172, v173
	v_add_f32_e32 v173, v174, v175
	v_fmac_f32_e32 v178, v116, v116
	v_fmac_f32_e32 v179, v118, v118
	v_add_f32_e32 v174, v176, v177
	v_add_f32_e32 v172, v172, v173
	v_add_f32_e32 v172, v172, v174
	v_add_f32_e32 v173, v178, v179
	v_add_f32_e32 v172, v173, v172
	v_mov_b32_e32 v173, v172
	s_nop 1
	v_permlane16_swap_b32_e32 v172, v173
	s_nop 1
	v_xor_b32_e32 v174, 32, v217
	v_cmp_lt_i32_e32 vcc, v174, v223
	s_waitcnt lgkmcnt(0)
	v_add_f32_e32 v172, v172, v173
	v_cndmask_b32_e32 v174, v217, v174, vcc
	v_lshlrev_b32_e32 v223, 2, v174
	v_mov_b32_e32 v173, v172
	s_nop 1
	v_permlane32_swap_b32_e32 v172, v173
	s_nop 1
	s_and_saveexec_b64 s[82:83], s[4:5]
	s_cbranch_execz .LBB0_510
	s_waitcnt lgkmcnt(0)
	v_add_f32_e32 v172, v172, v173
	ds_write_b32 v221, v172
.LBB0_510:
	s_or_b64 exec, exec, s[82:83]
	v_lshlrev_b32_e32 v172, 16, v148
	s_waitcnt lgkmcnt(0)
	v_and_b32_e32 v173, 0xffff0000, v148
	v_lshlrev_b32_e32 v148, 16, v149
	v_and_b32_e32 v149, 0xffff0000, v149
	v_lshlrev_b32_e32 v174, 16, v150
	v_and_b32_e32 v175, 0xffff0000, v150
	v_lshlrev_b32_e32 v150, 16, v151
	v_and_b32_e32 v151, 0xffff0000, v151
	v_lshlrev_b32_e32 v176, 16, v144
	v_and_b32_e32 v177, 0xffff0000, v144
	v_lshlrev_b32_e32 v178, 16, v145
	v_and_b32_e32 v179, 0xffff0000, v145
	v_lshlrev_b32_e32 v182, 16, v146
	v_and_b32_e32 v183, 0xffff0000, v146
	v_lshlrev_b32_e32 v184, 16, v147
	v_and_b32_e32 v185, 0xffff0000, v147
	v_pk_fma_f32 v[144:145], v[110:111], v[134:135], v[148:149]
	v_pk_fma_f32 v[146:147], v[108:109], v[132:133], v[172:173]
	v_pk_fma_f32 v[148:149], v[106:107], v[130:131], v[150:151]
	v_pk_fma_f32 v[150:151], v[104:105], v[128:129], v[174:175]
	v_mul_f32_e32 v108, v147, v147
	v_mul_f32_e32 v109, v145, v145
	v_mul_f32_e32 v104, v151, v151
	v_mul_f32_e32 v105, v149, v149
	v_fmac_f32_e32 v108, v146, v146
	v_fmac_f32_e32 v109, v144, v144
	v_fmac_f32_e32 v104, v150, v150
	v_fmac_f32_e32 v105, v148, v148
	v_add_f32_e32 v108, v108, v109
	v_add_f32_e32 v104, v104, v105
	v_add_f32_e32 v106, v108, v104
	v_pk_fma_f32 v[104:105], v[102:103], v[122:123], v[178:179]
	v_pk_fma_f32 v[108:109], v[100:101], v[120:121], v[176:177]
	v_mul_f32_e32 v101, v105, v105
	v_mul_f32_e32 v100, v109, v109
	v_fmac_f32_e32 v100, v108, v108
	v_fmac_f32_e32 v101, v104, v104
	v_add_f32_e32 v100, v100, v101
	v_add_f32_e32 v100, v106, v100
	v_pk_fma_f32 v[106:107], v[98:99], v[114:115], v[184:185]
	v_pk_fma_f32 v[110:111], v[96:97], v[112:113], v[182:183]
	v_mul_f32_e32 v97, v107, v107
	v_mul_f32_e32 v96, v111, v111
	v_fmac_f32_e32 v96, v110, v110
	v_fmac_f32_e32 v97, v106, v106
	v_add_f32_e32 v96, v96, v97
	v_add_f32_e32 v96, v96, v100
	v_mov_b32_e32 v97, v96
	s_nop 1
	v_permlane16_swap_b32_e32 v96, v97
	s_nop 1
	s_waitcnt lgkmcnt(0)
	v_add_f32_e32 v96, v96, v97
	v_mov_b32_e32 v97, v96
	s_nop 1
	v_permlane32_swap_b32_e32 v96, v97
	s_nop 1
	s_and_saveexec_b64 s[82:83], s[4:5]
	s_cbranch_execz .LBB0_512
	s_waitcnt lgkmcnt(0)
	v_add_f32_e32 v96, v96, v97
	ds_write_b32 v221, v96 offset:256
.LBB0_512:
	s_or_b64 exec, exec, s[82:83]
	v_or_b32_e32 v96, 32, v186
	s_waitcnt lgkmcnt(0)
	v_ashrrev_i32_e32 v97, 31, v96
	v_lshlrev_b64 v[184:185], 11, v[96:97]
	v_lshl_add_u64 v[96:97], v[190:191], 0, v[184:185]
	global_load_dwordx4 v[172:175], v[96:97], off
	global_load_dwordx4 v[176:179], v[96:97], off offset:256
	v_or_b32_e32 v96, 48, v186
	v_ashrrev_i32_e32 v97, 31, v96
	v_lshlrev_b64 v[182:183], 11, v[96:97]
	v_lshl_add_u64 v[96:97], v[190:191], 0, v[182:183]
	global_load_dwordx4 v[100:103], v[96:97], off
	s_nop 0
	global_load_dwordx4 v[96:99], v[96:97], off offset:256
	s_waitcnt vmcnt(3)
	v_lshlrev_b32_e32 v188, 16, v172
	v_and_b32_e32 v189, 0xffff0000, v172
	v_lshlrev_b32_e32 v172, 16, v173
	v_and_b32_e32 v173, 0xffff0000, v173
	v_lshlrev_b32_e32 v192, 16, v174
	v_and_b32_e32 v193, 0xffff0000, v174
	v_lshlrev_b32_e32 v224, 16, v175
	v_and_b32_e32 v225, 0xffff0000, v175
	s_waitcnt vmcnt(2)
	v_lshlrev_b32_e32 v226, 16, v176
	v_and_b32_e32 v227, 0xffff0000, v176
	v_lshlrev_b32_e32 v228, 16, v177
	v_and_b32_e32 v229, 0xffff0000, v177
	v_lshlrev_b32_e32 v230, 16, v178
	v_and_b32_e32 v231, 0xffff0000, v178
	v_lshlrev_b32_e32 v232, 16, v179
	v_and_b32_e32 v233, 0xffff0000, v179
	v_pk_fma_f32 v[172:173], v[94:95], v[134:135], v[172:173]
	v_pk_fma_f32 v[174:175], v[92:93], v[132:133], v[188:189]
	v_pk_fma_f32 v[176:177], v[90:91], v[130:131], v[224:225]
	v_pk_fma_f32 v[178:179], v[88:89], v[128:129], v[192:193]
	v_pk_fma_f32 v[86:87], v[86:87], v[122:123], v[228:229]
	v_pk_fma_f32 v[84:85], v[84:85], v[120:121], v[226:227]
	v_mul_f32_e32 v88, v175, v175
	v_mul_f32_e32 v89, v173, v173
	v_mul_f32_e32 v90, v179, v179
	v_mul_f32_e32 v91, v177, v177
	v_pk_fma_f32 v[82:83], v[82:83], v[114:115], v[232:233]
	v_pk_fma_f32 v[80:81], v[80:81], v[112:113], v[230:231]
	v_mul_f32_e32 v92, v85, v85
	v_mul_f32_e32 v93, v87, v87
	v_fmac_f32_e32 v88, v174, v174
	v_fmac_f32_e32 v89, v172, v172
	v_fmac_f32_e32 v90, v178, v178
	v_fmac_f32_e32 v91, v176, v176
	v_mul_f32_e32 v94, v81, v81
	v_mul_f32_e32 v95, v83, v83
	v_fmac_f32_e32 v92, v84, v84
	v_fmac_f32_e32 v93, v86, v86
	v_add_f32_e32 v88, v88, v89
	v_add_f32_e32 v89, v90, v91
	v_fmac_f32_e32 v94, v80, v80
	v_fmac_f32_e32 v95, v82, v82
	v_add_f32_e32 v90, v92, v93
	v_add_f32_e32 v88, v88, v89
	v_add_f32_e32 v88, v88, v90
	v_add_f32_e32 v89, v94, v95
	v_add_f32_e32 v88, v89, v88
	v_mov_b32_e32 v89, v88
	s_nop 1
	v_permlane16_swap_b32_e32 v88, v89
	s_nop 1
	s_waitcnt lgkmcnt(0)
	v_add_f32_e32 v88, v88, v89
	v_mov_b32_e32 v89, v88
	s_nop 1
	v_permlane32_swap_b32_e32 v88, v89
	s_nop 1
	s_and_saveexec_b64 s[82:83], s[4:5]
	s_cbranch_execz .LBB0_514
	s_waitcnt lgkmcnt(0)
	v_add_f32_e32 v88, v88, v89
	ds_write_b32 v221, v88 offset:512
.LBB0_514:
	s_or_b64 exec, exec, s[82:83]
	s_waitcnt vmcnt(1)
	v_lshlrev_b32_e32 v88, 16, v100
	s_waitcnt lgkmcnt(0)
	v_and_b32_e32 v89, 0xffff0000, v100
	v_lshlrev_b32_e32 v90, 16, v101
	v_and_b32_e32 v91, 0xffff0000, v101
	v_lshlrev_b32_e32 v92, 16, v102
	v_and_b32_e32 v93, 0xffff0000, v102
	v_lshlrev_b32_e32 v94, 16, v103
	v_and_b32_e32 v95, 0xffff0000, v103
	s_waitcnt vmcnt(0)
	v_lshlrev_b32_e32 v188, 16, v96
	v_and_b32_e32 v189, 0xffff0000, v96
	v_lshlrev_b32_e32 v192, 16, v97
	v_and_b32_e32 v193, 0xffff0000, v97
	v_lshlrev_b32_e32 v224, 16, v98
	v_and_b32_e32 v225, 0xffff0000, v98
	v_lshlrev_b32_e32 v226, 16, v99
	v_and_b32_e32 v227, 0xffff0000, v99
	v_pk_fma_f32 v[96:97], v[78:79], v[134:135], v[90:91]
	v_pk_fma_f32 v[98:99], v[76:77], v[132:133], v[88:89]
	v_pk_fma_f32 v[100:101], v[74:75], v[130:131], v[94:95]
	v_pk_fma_f32 v[102:103], v[72:73], v[128:129], v[92:93]
	v_mul_f32_e32 v76, v99, v99
	v_mul_f32_e32 v77, v97, v97
	v_mul_f32_e32 v72, v103, v103
	v_mul_f32_e32 v73, v101, v101
	v_fmac_f32_e32 v76, v98, v98
	v_fmac_f32_e32 v77, v96, v96
	v_fmac_f32_e32 v72, v102, v102
	v_fmac_f32_e32 v73, v100, v100
	v_add_f32_e32 v76, v76, v77
	v_add_f32_e32 v72, v72, v73
	v_add_f32_e32 v74, v76, v72
	v_pk_fma_f32 v[72:73], v[70:71], v[122:123], v[192:193]
	v_pk_fma_f32 v[76:77], v[68:69], v[120:121], v[188:189]
	v_mul_f32_e32 v69, v73, v73
	v_mul_f32_e32 v68, v77, v77
	v_fmac_f32_e32 v68, v76, v76
	v_fmac_f32_e32 v69, v72, v72
	v_add_f32_e32 v68, v68, v69
	v_add_f32_e32 v68, v74, v68
	v_pk_fma_f32 v[74:75], v[66:67], v[114:115], v[226:227]
	v_pk_fma_f32 v[78:79], v[64:65], v[112:113], v[224:225]
	v_mul_f32_e32 v65, v75, v75
	v_mul_f32_e32 v64, v79, v79
	v_fmac_f32_e32 v64, v78, v78
	v_fmac_f32_e32 v65, v74, v74
	v_add_f32_e32 v64, v64, v65
	v_add_f32_e32 v64, v64, v68
	v_mov_b32_e32 v65, v64
	s_nop 1
	v_permlane16_swap_b32_e32 v64, v65
	s_nop 1
	s_waitcnt lgkmcnt(0)
	v_add_f32_e32 v64, v64, v65
	v_mov_b32_e32 v65, v64
	s_nop 1
	v_permlane32_swap_b32_e32 v64, v65
	s_nop 1
	s_and_saveexec_b64 s[82:83], s[4:5]
	s_cbranch_execz .LBB0_516
	s_waitcnt lgkmcnt(0)
	v_add_f32_e32 v64, v64, v65
	ds_write_b32 v221, v64 offset:768
.LBB0_516:
	s_or_b64 exec, exec, s[82:83]
	s_waitcnt lgkmcnt(0)
	v_lshlrev_b64 v[64:65], 11, v[186:187]
	s_mov_b64 s[62:63], 0x40000
	v_lshl_add_u64 v[192:193], v[64:65], 0, s[62:63]
	v_lshl_add_u64 v[66:67], v[190:191], 0, v[192:193]
	global_load_dwordx4 v[88:91], v[66:67], off
	global_load_dwordx4 v[92:95], v[66:67], off offset:256
	s_mov_b64 s[62:63], 0x48000
	v_lshl_add_u64 v[188:189], v[64:65], 0, s[62:63]
	v_lshl_add_u64 v[64:65], v[190:191], 0, v[188:189]
	global_load_dwordx4 v[68:71], v[64:65], off
	s_nop 0
	global_load_dwordx4 v[64:67], v[64:65], off offset:256
	s_waitcnt vmcnt(3)
	v_lshlrev_b32_e32 v224, 16, v88
	v_and_b32_e32 v225, 0xffff0000, v88
	v_lshlrev_b32_e32 v88, 16, v89
	v_and_b32_e32 v89, 0xffff0000, v89
	v_lshlrev_b32_e32 v226, 16, v90
	v_and_b32_e32 v227, 0xffff0000, v90
	v_lshlrev_b32_e32 v228, 16, v91
	v_and_b32_e32 v229, 0xffff0000, v91
	s_waitcnt vmcnt(2)
	v_lshlrev_b32_e32 v230, 16, v92
	v_and_b32_e32 v231, 0xffff0000, v92
	v_lshlrev_b32_e32 v232, 16, v93
	v_and_b32_e32 v233, 0xffff0000, v93
	v_lshlrev_b32_e32 v234, 16, v94
	v_and_b32_e32 v235, 0xffff0000, v94
	v_lshlrev_b32_e32 v236, 16, v95
	v_and_b32_e32 v237, 0xffff0000, v95
	v_pk_fma_f32 v[88:89], v[62:63], v[134:135], v[88:89]
	v_pk_fma_f32 v[90:91], v[60:61], v[132:133], v[224:225]
	v_pk_fma_f32 v[92:93], v[58:59], v[130:131], v[228:229]
	v_pk_fma_f32 v[94:95], v[56:57], v[128:129], v[226:227]
	v_pk_fma_f32 v[54:55], v[54:55], v[122:123], v[232:233]
	v_pk_fma_f32 v[52:53], v[52:53], v[120:121], v[230:231]
	v_mul_f32_e32 v56, v91, v91
	v_mul_f32_e32 v57, v89, v89
	v_mul_f32_e32 v58, v95, v95
	v_mul_f32_e32 v59, v93, v93
	v_pk_fma_f32 v[50:51], v[50:51], v[114:115], v[236:237]
	v_pk_fma_f32 v[48:49], v[48:49], v[112:113], v[234:235]
	v_mul_f32_e32 v60, v53, v53
	v_mul_f32_e32 v61, v55, v55
	v_fmac_f32_e32 v56, v90, v90
	v_fmac_f32_e32 v57, v88, v88
	v_fmac_f32_e32 v58, v94, v94
	v_fmac_f32_e32 v59, v92, v92
	v_mul_f32_e32 v62, v49, v49
	v_mul_f32_e32 v63, v51, v51
	v_fmac_f32_e32 v60, v52, v52
	v_fmac_f32_e32 v61, v54, v54
	v_add_f32_e32 v56, v56, v57
	v_add_f32_e32 v57, v58, v59
	v_fmac_f32_e32 v62, v48, v48
	v_fmac_f32_e32 v63, v50, v50
	v_add_f32_e32 v58, v60, v61
	v_add_f32_e32 v56, v56, v57
	v_add_f32_e32 v56, v56, v58
	v_add_f32_e32 v57, v62, v63
	v_add_f32_e32 v56, v57, v56
	v_mov_b32_e32 v57, v56
	s_nop 1
	v_permlane16_swap_b32_e32 v56, v57
	s_nop 1
	s_waitcnt lgkmcnt(0)
	v_add_f32_e32 v56, v56, v57
	v_mov_b32_e32 v57, v56
	s_nop 1
	v_permlane32_swap_b32_e32 v56, v57
	s_nop 1
	s_and_saveexec_b64 s[82:83], s[4:5]
	s_cbranch_execz .LBB0_518
	s_waitcnt lgkmcnt(0)
	v_add_f32_e32 v56, v56, v57
	ds_write_b32 v221, v56 offset:2048
.LBB0_518:
	s_or_b64 exec, exec, s[82:83]
	s_waitcnt vmcnt(1)
	v_lshlrev_b32_e32 v58, 16, v68
	v_and_b32_e32 v59, 0xffff0000, v68
	v_lshlrev_b32_e32 v56, 16, v69
	s_waitcnt lgkmcnt(0)
	v_and_b32_e32 v57, 0xffff0000, v69
	v_lshlrev_b32_e32 v62, 16, v70
	v_and_b32_e32 v63, 0xffff0000, v70
	v_lshlrev_b32_e32 v60, 16, v71
	v_and_b32_e32 v61, 0xffff0000, v71
	v_pk_fma_f32 v[56:57], v[46:47], v[134:135], v[56:57]
	v_pk_fma_f32 v[58:59], v[44:45], v[132:133], v[58:59]
	v_pk_fma_f32 v[60:61], v[42:43], v[130:131], v[60:61]
	v_pk_fma_f32 v[62:63], v[40:41], v[128:129], v[62:63]
	v_mul_f32_e32 v44, v59, v59
	v_mul_f32_e32 v45, v57, v57
	v_mul_f32_e32 v40, v63, v63
	v_mul_f32_e32 v41, v61, v61
	v_fmac_f32_e32 v44, v58, v58
	v_fmac_f32_e32 v45, v56, v56
	v_fmac_f32_e32 v40, v62, v62
	v_fmac_f32_e32 v41, v60, v60
	s_waitcnt vmcnt(0)
	v_lshlrev_b32_e32 v68, 16, v64
	v_and_b32_e32 v69, 0xffff0000, v64
	v_lshlrev_b32_e32 v64, 16, v65
	v_and_b32_e32 v65, 0xffff0000, v65
	v_add_f32_e32 v44, v44, v45
	v_add_f32_e32 v40, v40, v41
	v_add_f32_e32 v44, v44, v40
	v_pk_fma_f32 v[40:41], v[38:39], v[122:123], v[64:65]
	v_pk_fma_f32 v[42:43], v[36:37], v[120:121], v[68:69]
	v_mul_f32_e32 v37, v41, v41
	v_mul_f32_e32 v36, v43, v43
	v_fmac_f32_e32 v36, v42, v42
	v_fmac_f32_e32 v37, v40, v40
	v_lshlrev_b32_e32 v70, 16, v66
	v_and_b32_e32 v71, 0xffff0000, v66
	v_lshlrev_b32_e32 v66, 16, v67
	v_and_b32_e32 v67, 0xffff0000, v67
	v_add_f32_e32 v36, v36, v37
	v_add_f32_e32 v36, v44, v36
	v_pk_fma_f32 v[44:45], v[34:35], v[114:115], v[66:67]
	v_pk_fma_f32 v[46:47], v[32:33], v[112:113], v[70:71]
	v_mul_f32_e32 v33, v45, v45
	v_mul_f32_e32 v32, v47, v47
	v_fmac_f32_e32 v32, v46, v46
	v_fmac_f32_e32 v33, v44, v44
	v_add_f32_e32 v32, v32, v33
	v_add_f32_e32 v32, v32, v36
	v_mov_b32_e32 v33, v32
	s_nop 1
	v_permlane16_swap_b32_e32 v32, v33
	s_nop 1
	s_waitcnt lgkmcnt(0)
	v_add_f32_e32 v32, v32, v33
	v_mov_b32_e32 v33, v32
	s_nop 1
	v_permlane32_swap_b32_e32 v32, v33
	s_nop 1
	s_and_saveexec_b64 s[82:83], s[4:5]
	s_cbranch_execz .LBB0_520
	s_waitcnt lgkmcnt(0)
	v_add_f32_e32 v32, v32, v33
	ds_write_b32 v221, v32 offset:2304
.LBB0_520:
	s_or_b64 exec, exec, s[82:83]
	s_waitcnt lgkmcnt(0)
	v_lshlrev_b64 v[32:33], 11, v[186:187]
	s_mov_b64 s[62:63], 0x50000
	v_lshl_add_u64 v[68:69], v[32:33], 0, s[62:63]
	v_lshl_add_u64 v[34:35], v[190:191], 0, v[68:69]
	global_load_dwordx4 v[224:227], v[34:35], off
	global_load_dwordx4 v[228:231], v[34:35], off offset:256
	s_mov_b64 s[62:63], 0x58000
	v_lshl_add_u64 v[66:67], v[32:33], 0, s[62:63]
	v_lshl_add_u64 v[32:33], v[190:191], 0, v[66:67]
	global_load_dwordx4 v[36:39], v[32:33], off
	s_nop 0
	global_load_dwordx4 v[32:35], v[32:33], off offset:256
	s_waitcnt vmcnt(3)
	v_lshlrev_b32_e32 v64, 16, v224
	v_and_b32_e32 v65, 0xffff0000, v224
	v_lshlrev_b32_e32 v70, 16, v225
	v_and_b32_e32 v71, 0xffff0000, v225
	v_lshlrev_b32_e32 v186, 16, v226
	v_and_b32_e32 v187, 0xffff0000, v226
	v_lshlrev_b32_e32 v190, 16, v227
	v_and_b32_e32 v191, 0xffff0000, v227
	s_waitcnt vmcnt(2)
	v_lshlrev_b32_e32 v224, 16, v228
	v_and_b32_e32 v225, 0xffff0000, v228
	v_lshlrev_b32_e32 v226, 16, v229
	v_and_b32_e32 v227, 0xffff0000, v229
	v_pk_fma_f32 v[30:31], v[30:31], v[134:135], v[70:71]
	v_pk_fma_f32 v[28:29], v[28:29], v[132:133], v[64:65]
	v_pk_fma_f32 v[26:27], v[26:27], v[130:131], v[190:191]
	v_pk_fma_f32 v[24:25], v[24:25], v[128:129], v[186:187]
	v_lshlrev_b32_e32 v228, 16, v230
	v_and_b32_e32 v229, 0xffff0000, v230
	v_lshlrev_b32_e32 v230, 16, v231
	v_and_b32_e32 v231, 0xffff0000, v231
	v_pk_fma_f32 v[22:23], v[22:23], v[122:123], v[226:227]
	v_pk_fma_f32 v[20:21], v[20:21], v[120:121], v[224:225]
	v_mul_f32_e32 v64, v29, v29
	v_mul_f32_e32 v65, v31, v31
	v_mul_f32_e32 v70, v25, v25
	v_mul_f32_e32 v71, v27, v27
	v_pk_fma_f32 v[18:19], v[18:19], v[114:115], v[230:231]
	v_pk_fma_f32 v[16:17], v[16:17], v[112:113], v[228:229]
	v_mul_f32_e32 v186, v21, v21
	v_mul_f32_e32 v187, v23, v23
	v_fmac_f32_e32 v64, v28, v28
	v_fmac_f32_e32 v65, v30, v30
	v_fmac_f32_e32 v70, v24, v24
	v_fmac_f32_e32 v71, v26, v26
	v_mul_f32_e32 v190, v17, v17
	v_mul_f32_e32 v191, v19, v19
	v_fmac_f32_e32 v186, v20, v20
	v_fmac_f32_e32 v187, v22, v22
	v_add_f32_e32 v64, v64, v65
	v_add_f32_e32 v65, v70, v71
	v_fmac_f32_e32 v190, v16, v16
	v_fmac_f32_e32 v191, v18, v18
	v_add_f32_e32 v70, v186, v187
	v_add_f32_e32 v64, v64, v65
	v_add_f32_e32 v64, v64, v70
	v_add_f32_e32 v65, v190, v191
	v_add_f32_e32 v64, v65, v64
	v_mov_b32_e32 v65, v64
	s_nop 1
	v_permlane16_swap_b32_e32 v64, v65
	s_nop 1
	s_waitcnt lgkmcnt(0)
	v_add_f32_e32 v64, v64, v65
	v_mov_b32_e32 v65, v64
	s_nop 1
	v_permlane32_swap_b32_e32 v64, v65
	s_nop 1
	s_and_saveexec_b64 s[82:83], s[4:5]
	s_cbranch_execz .LBB0_522
	s_waitcnt lgkmcnt(0)
	v_add_f32_e32 v64, v64, v65
	ds_write_b32 v221, v64 offset:2560
.LBB0_522:
	s_or_b64 exec, exec, s[82:83]
	s_waitcnt vmcnt(1)
	v_lshlrev_b32_e32 v64, 16, v36
	s_waitcnt lgkmcnt(0)
	v_and_b32_e32 v65, 0xffff0000, v36
	v_lshlrev_b32_e32 v36, 16, v37
	v_and_b32_e32 v37, 0xffff0000, v37
	v_lshlrev_b32_e32 v70, 16, v38
	v_and_b32_e32 v71, 0xffff0000, v38
	v_lshlrev_b32_e32 v38, 16, v39
	v_and_b32_e32 v39, 0xffff0000, v39
	s_waitcnt vmcnt(0)
	v_lshlrev_b32_e32 v186, 16, v32
	v_and_b32_e32 v187, 0xffff0000, v32
	v_lshlrev_b32_e32 v190, 16, v33
	v_and_b32_e32 v191, 0xffff0000, v33
	v_lshlrev_b32_e32 v224, 16, v34
	v_and_b32_e32 v225, 0xffff0000, v34
	v_lshlrev_b32_e32 v226, 16, v35
	v_and_b32_e32 v227, 0xffff0000, v35
	v_pk_fma_f32 v[32:33], v[14:15], v[134:135], v[36:37]
	v_pk_fma_f32 v[34:35], v[12:13], v[132:133], v[64:65]
	v_pk_fma_f32 v[36:37], v[10:11], v[130:131], v[38:39]
	v_pk_fma_f32 v[38:39], v[8:9], v[128:129], v[70:71]
	v_mul_f32_e32 v12, v35, v35
	v_mul_f32_e32 v13, v33, v33
	v_mul_f32_e32 v8, v39, v39
	v_mul_f32_e32 v9, v37, v37
	v_fmac_f32_e32 v12, v34, v34
	v_fmac_f32_e32 v13, v32, v32
	v_fmac_f32_e32 v8, v38, v38
	v_fmac_f32_e32 v9, v36, v36
	v_add_f32_e32 v12, v12, v13
	v_add_f32_e32 v8, v8, v9
	v_add_f32_e32 v12, v12, v8
	v_pk_fma_f32 v[8:9], v[6:7], v[122:123], v[190:191]
	v_pk_fma_f32 v[10:11], v[4:5], v[120:121], v[186:187]
	v_mul_f32_e32 v5, v9, v9
	v_mul_f32_e32 v4, v11, v11
	v_fmac_f32_e32 v4, v10, v10
	v_fmac_f32_e32 v5, v8, v8
	v_add_f32_e32 v4, v4, v5
	v_add_f32_e32 v4, v12, v4
	v_pk_fma_f32 v[12:13], v[2:3], v[114:115], v[226:227]
	v_pk_fma_f32 v[14:15], v[0:1], v[112:113], v[224:225]
	v_mul_f32_e32 v1, v13, v13
	v_mul_f32_e32 v0, v15, v15
	v_fmac_f32_e32 v0, v14, v14
	v_fmac_f32_e32 v1, v12, v12
	v_add_f32_e32 v0, v0, v1
	v_add_f32_e32 v0, v0, v4
	v_mov_b32_e32 v1, v0
	s_nop 1
	v_permlane16_swap_b32_e32 v0, v1
	s_nop 1
	s_waitcnt lgkmcnt(0)
	v_add_f32_e32 v0, v0, v1
	v_mov_b32_e32 v1, v0
	s_nop 1
	v_permlane32_swap_b32_e32 v0, v1
	s_nop 1
	s_and_saveexec_b64 s[82:83], s[4:5]
	s_cbranch_execz .LBB0_524
	s_waitcnt lgkmcnt(0)
	v_add_f32_e32 v0, v0, v1
	ds_write_b32 v221, v0 offset:2816

.LBB0_1789:
	s_lshl_b32 s61, s0, 8
	s_add_i32 s1, s61, 0xfffff000
	v_lshl_add_u32 v170, s68, 8, v190
	v_add_u32_e32 v178, s61, v188
	s_lshr_b32 s1, s1, 11
	v_ashrrev_i32_e32 v171, 31, v170
	v_ashrrev_i32_e32 v179, 31, v178
	s_mulk_i32 s1, 0x1800
	s_cmp_gt_i32 s0, 15
	v_lshl_add_u64 v[180:181], v[170:171], 1, s[20:21]
	v_lshlrev_b64 v[168:169], 11, v[178:179]
	s_cselect_b32 s16, s1, 0x6000
	v_lshl_add_u64 v[112:113], v[180:181], 0, v[168:169]
	s_lshl_b64 s[70:71], s[16:17], 2
	global_load_dwordx4 v[174:177], v[112:113], off
	global_load_dwordx4 v[182:185], v[112:113], off offset:256
	s_add_u32 s58, s43, s70
	s_addc_u32 s59, s76, s71
	v_lshl_add_u64 v[112:113], v[170:171], 2, s[58:59]
	global_load_dwordx4 v[132:135], v[112:113], off
	global_load_dwordx4 v[128:131], v[112:113], off offset:16
	global_load_dwordx4 v[120:123], v[112:113], off offset:512
	s_nop 0
	global_load_dwordx4 v[112:115], v[112:113], off offset:528
	v_or_b32_e32 v144, 16, v178
	v_ashrrev_i32_e32 v145, 31, v144
	v_lshlrev_b64 v[172:173], 11, v[144:145]
	v_lshl_add_u64 v[144:145], v[180:181], 0, v[172:173]
	global_load_dwordx4 v[148:151], v[144:145], off
	s_nop 0
	global_load_dwordx4 v[144:147], v[144:145], off offset:256
	v_and_b32_e32 v187, 64, v211
	v_xor_b32_e32 v186, 16, v211
	v_add_u32_e32 v217, 64, v187
	v_cmp_lt_i32_e32 vcc, v186, v217
	s_waitcnt vmcnt(0)
	v_and_b32_e32 v187, 0xffff0000, v174
	v_cndmask_b32_e32 v186, v211, v186, vcc
	v_lshlrev_b32_e32 v216, 2, v186
	v_lshlrev_b32_e32 v186, 16, v174
	v_lshlrev_b32_e32 v174, 16, v175
	v_and_b32_e32 v175, 0xffff0000, v175
	v_lshlrev_b32_e32 v218, 16, v176
	v_and_b32_e32 v219, 0xffff0000, v176
	v_lshlrev_b32_e32 v176, 16, v177
	v_and_b32_e32 v177, 0xffff0000, v177
	v_lshlrev_b32_e32 v220, 16, v182
	v_and_b32_e32 v221, 0xffff0000, v182
	v_lshlrev_b32_e32 v182, 16, v183
	v_and_b32_e32 v183, 0xffff0000, v183
	v_pk_fma_f32 v[142:143], v[142:143], v[134:135], v[174:175]
	v_pk_fma_f32 v[140:141], v[140:141], v[132:133], v[186:187]
	v_pk_fma_f32 v[138:139], v[138:139], v[130:131], v[176:177]
	v_pk_fma_f32 v[136:137], v[136:137], v[128:129], v[218:219]
	v_lshlrev_b32_e32 v222, 16, v184
	v_and_b32_e32 v223, 0xffff0000, v184
	v_lshlrev_b32_e32 v184, 16, v185
	v_and_b32_e32 v185, 0xffff0000, v185
	v_pk_fma_f32 v[126:127], v[126:127], v[122:123], v[182:183]
	v_pk_fma_f32 v[124:125], v[124:125], v[120:121], v[220:221]
	v_mul_f32_e32 v174, v141, v141
	v_mul_f32_e32 v175, v143, v143
	v_mul_f32_e32 v176, v137, v137
	v_mul_f32_e32 v177, v139, v139
	v_pk_fma_f32 v[118:119], v[118:119], v[114:115], v[184:185]
	v_pk_fma_f32 v[116:117], v[116:117], v[112:113], v[222:223]
	v_mul_f32_e32 v182, v125, v125
	v_mul_f32_e32 v183, v127, v127
	v_fmac_f32_e32 v174, v140, v140
	v_fmac_f32_e32 v175, v142, v142
	v_fmac_f32_e32 v176, v136, v136
	v_fmac_f32_e32 v177, v138, v138
	v_mul_f32_e32 v184, v117, v117
	v_mul_f32_e32 v185, v119, v119
	v_fmac_f32_e32 v182, v124, v124
	v_fmac_f32_e32 v183, v126, v126
	v_add_f32_e32 v174, v174, v175
	v_add_f32_e32 v175, v176, v177
	v_fmac_f32_e32 v184, v116, v116
	v_fmac_f32_e32 v185, v118, v118
	v_add_f32_e32 v176, v182, v183
	v_add_f32_e32 v174, v174, v175
	v_add_f32_e32 v174, v174, v176
	v_add_f32_e32 v175, v184, v185
	v_add_f32_e32 v174, v175, v174
	v_mov_b32_e32 v175, v174
	s_nop 1
	v_permlane16_swap_b32_e32 v174, v175
	s_nop 1
	v_xor_b32_e32 v176, 32, v211
	v_cmp_lt_i32_e32 vcc, v176, v217
	s_waitcnt lgkmcnt(0)
	v_add_f32_e32 v174, v174, v175
	v_cndmask_b32_e32 v176, v211, v176, vcc
	v_lshlrev_b32_e32 v217, 2, v176
	v_mov_b32_e32 v175, v174
	s_nop 1
	v_permlane32_swap_b32_e32 v174, v175
	s_nop 1
	s_and_saveexec_b64 s[72:73], s[4:5]
	s_cbranch_execz .LBB0_1791
	s_waitcnt lgkmcnt(0)
	v_add_f32_e32 v174, v174, v175
	ds_write_b32 v215, v174
.LBB0_1791:
	s_or_b64 exec, exec, s[72:73]
	v_lshlrev_b32_e32 v174, 16, v148
	s_waitcnt lgkmcnt(0)
	v_and_b32_e32 v175, 0xffff0000, v148
	v_lshlrev_b32_e32 v148, 16, v149
	v_and_b32_e32 v149, 0xffff0000, v149
	v_lshlrev_b32_e32 v176, 16, v150
	v_and_b32_e32 v177, 0xffff0000, v150
	v_lshlrev_b32_e32 v150, 16, v151
	v_and_b32_e32 v151, 0xffff0000, v151
	v_lshlrev_b32_e32 v182, 16, v144
	v_and_b32_e32 v183, 0xffff0000, v144
	v_lshlrev_b32_e32 v184, 16, v145
	v_and_b32_e32 v185, 0xffff0000, v145
	v_lshlrev_b32_e32 v186, 16, v146
	v_and_b32_e32 v187, 0xffff0000, v146
	v_lshlrev_b32_e32 v218, 16, v147
	v_and_b32_e32 v219, 0xffff0000, v147
	v_pk_fma_f32 v[144:145], v[110:111], v[134:135], v[148:149]
	v_pk_fma_f32 v[146:147], v[108:109], v[132:133], v[174:175]
	v_pk_fma_f32 v[148:149], v[106:107], v[130:131], v[150:151]
	v_pk_fma_f32 v[150:151], v[104:105], v[128:129], v[176:177]
	v_mul_f32_e32 v108, v147, v147
	v_mul_f32_e32 v109, v145, v145
	v_mul_f32_e32 v104, v151, v151
	v_mul_f32_e32 v105, v149, v149
	v_fmac_f32_e32 v108, v146, v146
	v_fmac_f32_e32 v109, v144, v144
	v_fmac_f32_e32 v104, v150, v150
	v_fmac_f32_e32 v105, v148, v148
	v_add_f32_e32 v108, v108, v109
	v_add_f32_e32 v104, v104, v105
	v_add_f32_e32 v108, v108, v104
	v_pk_fma_f32 v[104:105], v[102:103], v[122:123], v[184:185]
	v_pk_fma_f32 v[106:107], v[100:101], v[120:121], v[182:183]
	v_mul_f32_e32 v101, v105, v105
	v_mul_f32_e32 v100, v107, v107
	v_fmac_f32_e32 v100, v106, v106
	v_fmac_f32_e32 v101, v104, v104
	v_add_f32_e32 v100, v100, v101
	v_add_f32_e32 v100, v108, v100
	v_pk_fma_f32 v[108:109], v[98:99], v[114:115], v[218:219]
	v_pk_fma_f32 v[110:111], v[96:97], v[112:113], v[186:187]
	v_mul_f32_e32 v97, v109, v109
	v_mul_f32_e32 v96, v111, v111
	v_fmac_f32_e32 v96, v110, v110
	v_fmac_f32_e32 v97, v108, v108
	v_add_f32_e32 v96, v96, v97
	v_add_f32_e32 v96, v96, v100
	v_mov_b32_e32 v97, v96
	s_nop 1
	v_permlane16_swap_b32_e32 v96, v97
	s_nop 1
	s_waitcnt lgkmcnt(0)
	v_add_f32_e32 v96, v96, v97
	v_mov_b32_e32 v97, v96
	s_nop 1
	v_permlane32_swap_b32_e32 v96, v97
	s_nop 1
	s_and_saveexec_b64 s[72:73], s[4:5]
	s_cbranch_execz .LBB0_1793
	s_waitcnt lgkmcnt(0)
	v_add_f32_e32 v96, v96, v97
	ds_write_b32 v215, v96 offset:256
.LBB0_1793:
	s_or_b64 exec, exec, s[72:73]
	v_or_b32_e32 v96, 32, v178
	s_waitcnt lgkmcnt(0)
	v_ashrrev_i32_e32 v97, 31, v96
	v_lshlrev_b64 v[176:177], 11, v[96:97]
	v_lshl_add_u64 v[96:97], v[180:181], 0, v[176:177]
	global_load_dwordx4 v[182:185], v[96:97], off
	global_load_dwordx4 v[218:221], v[96:97], off offset:256
	v_or_b32_e32 v96, 48, v178
	v_ashrrev_i32_e32 v97, 31, v96
	v_lshlrev_b64 v[174:175], 11, v[96:97]
	v_lshl_add_u64 v[96:97], v[180:181], 0, v[174:175]
	global_load_dwordx4 v[100:103], v[96:97], off
	s_nop 0
	global_load_dwordx4 v[96:99], v[96:97], off offset:256
	s_waitcnt vmcnt(3)
	v_lshlrev_b32_e32 v186, 16, v182
	v_and_b32_e32 v187, 0xffff0000, v182
	v_lshlrev_b32_e32 v182, 16, v183
	v_and_b32_e32 v183, 0xffff0000, v183
	v_lshlrev_b32_e32 v222, 16, v184
	v_and_b32_e32 v223, 0xffff0000, v184
	v_lshlrev_b32_e32 v184, 16, v185
	v_and_b32_e32 v185, 0xffff0000, v185
	s_waitcnt vmcnt(2)
	v_lshlrev_b32_e32 v224, 16, v218
	v_and_b32_e32 v225, 0xffff0000, v218
	v_lshlrev_b32_e32 v218, 16, v219
	v_and_b32_e32 v219, 0xffff0000, v219
	v_pk_fma_f32 v[94:95], v[94:95], v[134:135], v[182:183]
	v_pk_fma_f32 v[92:93], v[92:93], v[132:133], v[186:187]
	v_pk_fma_f32 v[90:91], v[90:91], v[130:131], v[184:185]
	v_pk_fma_f32 v[88:89], v[88:89], v[128:129], v[222:223]
	v_lshlrev_b32_e32 v226, 16, v220
	v_and_b32_e32 v227, 0xffff0000, v220
	v_lshlrev_b32_e32 v220, 16, v221
	v_and_b32_e32 v221, 0xffff0000, v221
	v_pk_fma_f32 v[86:87], v[86:87], v[122:123], v[218:219]
	v_pk_fma_f32 v[84:85], v[84:85], v[120:121], v[224:225]
	v_mul_f32_e32 v182, v93, v93
	v_mul_f32_e32 v183, v95, v95
	v_mul_f32_e32 v184, v89, v89
	v_mul_f32_e32 v185, v91, v91
	v_pk_fma_f32 v[82:83], v[82:83], v[114:115], v[220:221]
	v_pk_fma_f32 v[80:81], v[80:81], v[112:113], v[226:227]
	v_mul_f32_e32 v186, v85, v85
	v_mul_f32_e32 v187, v87, v87
	v_fmac_f32_e32 v182, v92, v92
	v_fmac_f32_e32 v183, v94, v94
	v_fmac_f32_e32 v184, v88, v88
	v_fmac_f32_e32 v185, v90, v90
	v_mul_f32_e32 v218, v81, v81
	v_mul_f32_e32 v219, v83, v83
	v_fmac_f32_e32 v186, v84, v84
	v_fmac_f32_e32 v187, v86, v86
	v_add_f32_e32 v182, v182, v183
	v_add_f32_e32 v183, v184, v185
	v_fmac_f32_e32 v218, v80, v80
	v_fmac_f32_e32 v219, v82, v82
	v_add_f32_e32 v184, v186, v187
	v_add_f32_e32 v182, v182, v183
	v_add_f32_e32 v182, v182, v184
	v_add_f32_e32 v183, v218, v219
	v_add_f32_e32 v182, v183, v182
	v_mov_b32_e32 v183, v182
	s_nop 1
	v_permlane16_swap_b32_e32 v182, v183
	s_nop 1
	s_waitcnt lgkmcnt(0)
	v_add_f32_e32 v182, v182, v183
	v_mov_b32_e32 v183, v182
	s_nop 1
	v_permlane32_swap_b32_e32 v182, v183
	s_nop 1
	s_and_saveexec_b64 s[72:73], s[4:5]
	s_cbranch_execz .LBB0_1795
	s_waitcnt lgkmcnt(0)
	v_add_f32_e32 v182, v182, v183
	ds_write_b32 v215, v182 offset:512
.LBB0_1795:
	s_or_b64 exec, exec, s[72:73]
	s_waitcnt vmcnt(1)
	v_lshlrev_b32_e32 v182, 16, v100
	s_waitcnt lgkmcnt(0)
	v_and_b32_e32 v183, 0xffff0000, v100
	v_lshlrev_b32_e32 v100, 16, v101
	v_and_b32_e32 v101, 0xffff0000, v101
	v_lshlrev_b32_e32 v184, 16, v102
	v_and_b32_e32 v185, 0xffff0000, v102
	v_lshlrev_b32_e32 v102, 16, v103
	v_and_b32_e32 v103, 0xffff0000, v103
	s_waitcnt vmcnt(0)
	v_lshlrev_b32_e32 v186, 16, v96
	v_and_b32_e32 v187, 0xffff0000, v96
	v_lshlrev_b32_e32 v218, 16, v97
	v_and_b32_e32 v219, 0xffff0000, v97
	v_lshlrev_b32_e32 v220, 16, v98
	v_and_b32_e32 v221, 0xffff0000, v98
	v_lshlrev_b32_e32 v222, 16, v99
	v_and_b32_e32 v223, 0xffff0000, v99
	v_pk_fma_f32 v[96:97], v[78:79], v[134:135], v[100:101]
	v_pk_fma_f32 v[98:99], v[76:77], v[132:133], v[182:183]
	v_pk_fma_f32 v[100:101], v[74:75], v[130:131], v[102:103]
	v_pk_fma_f32 v[102:103], v[72:73], v[128:129], v[184:185]
	v_mul_f32_e32 v76, v99, v99
	v_mul_f32_e32 v77, v97, v97
	v_mul_f32_e32 v72, v103, v103
	v_mul_f32_e32 v73, v101, v101
	v_fmac_f32_e32 v76, v98, v98
	v_fmac_f32_e32 v77, v96, v96
	v_fmac_f32_e32 v72, v102, v102
	v_fmac_f32_e32 v73, v100, v100
	v_add_f32_e32 v76, v76, v77
	v_add_f32_e32 v72, v72, v73
	v_add_f32_e32 v76, v76, v72
	v_pk_fma_f32 v[72:73], v[70:71], v[122:123], v[218:219]
	v_pk_fma_f32 v[74:75], v[68:69], v[120:121], v[186:187]
	v_mul_f32_e32 v69, v73, v73
	v_mul_f32_e32 v68, v75, v75
	v_fmac_f32_e32 v68, v74, v74
	v_fmac_f32_e32 v69, v72, v72
	v_add_f32_e32 v68, v68, v69
	v_add_f32_e32 v68, v76, v68
	v_pk_fma_f32 v[76:77], v[66:67], v[114:115], v[222:223]
	v_pk_fma_f32 v[78:79], v[64:65], v[112:113], v[220:221]
	v_mul_f32_e32 v65, v77, v77
	v_mul_f32_e32 v64, v79, v79
	v_fmac_f32_e32 v64, v78, v78
	v_fmac_f32_e32 v65, v76, v76
	v_add_f32_e32 v64, v64, v65
	v_add_f32_e32 v64, v64, v68
	v_mov_b32_e32 v65, v64
	s_nop 1
	v_permlane16_swap_b32_e32 v64, v65
	s_nop 1
	s_waitcnt lgkmcnt(0)
	v_add_f32_e32 v64, v64, v65
	v_mov_b32_e32 v65, v64
	s_nop 1
	v_permlane32_swap_b32_e32 v64, v65
	s_nop 1
	s_and_saveexec_b64 s[72:73], s[4:5]
	s_cbranch_execz .LBB0_1797
	s_waitcnt lgkmcnt(0)
	v_add_f32_e32 v64, v64, v65
	ds_write_b32 v215, v64 offset:768
.LBB0_1797:
	s_or_b64 exec, exec, s[72:73]
	s_waitcnt lgkmcnt(0)
	v_lshlrev_b64 v[64:65], 11, v[178:179]
	s_mov_b64 s[58:59], 0x40000
	v_lshl_add_u64 v[184:185], v[64:65], 0, s[58:59]
	v_lshl_add_u64 v[66:67], v[180:181], 0, v[184:185]
	global_load_dwordx4 v[218:221], v[66:67], off
	global_load_dwordx4 v[222:225], v[66:67], off offset:256
	s_mov_b64 s[58:59], 0x48000
	v_lshl_add_u64 v[182:183], v[64:65], 0, s[58:59]
	v_lshl_add_u64 v[64:65], v[180:181], 0, v[182:183]
	global_load_dwordx4 v[68:71], v[64:65], off
	s_nop 0
	global_load_dwordx4 v[64:67], v[64:65], off offset:256
	s_waitcnt vmcnt(3)
	v_lshlrev_b32_e32 v186, 16, v218
	v_and_b32_e32 v187, 0xffff0000, v218
	v_lshlrev_b32_e32 v218, 16, v219
	v_and_b32_e32 v219, 0xffff0000, v219
	v_lshlrev_b32_e32 v226, 16, v220
	v_and_b32_e32 v227, 0xffff0000, v220
	v_lshlrev_b32_e32 v220, 16, v221
	v_and_b32_e32 v221, 0xffff0000, v221
	s_waitcnt vmcnt(2)
	v_lshlrev_b32_e32 v228, 16, v222
	v_and_b32_e32 v229, 0xffff0000, v222
	v_lshlrev_b32_e32 v222, 16, v223
	v_and_b32_e32 v223, 0xffff0000, v223
	v_pk_fma_f32 v[62:63], v[62:63], v[134:135], v[218:219]
	v_pk_fma_f32 v[60:61], v[60:61], v[132:133], v[186:187]
	v_pk_fma_f32 v[58:59], v[58:59], v[130:131], v[220:221]
	v_pk_fma_f32 v[56:57], v[56:57], v[128:129], v[226:227]
	v_lshlrev_b32_e32 v230, 16, v224
	v_and_b32_e32 v231, 0xffff0000, v224
	v_lshlrev_b32_e32 v224, 16, v225
	v_and_b32_e32 v225, 0xffff0000, v225
	v_pk_fma_f32 v[54:55], v[54:55], v[122:123], v[222:223]
	v_pk_fma_f32 v[52:53], v[52:53], v[120:121], v[228:229]
	v_mul_f32_e32 v186, v61, v61
	v_mul_f32_e32 v187, v63, v63
	v_mul_f32_e32 v218, v57, v57
	v_mul_f32_e32 v219, v59, v59
	v_pk_fma_f32 v[50:51], v[50:51], v[114:115], v[224:225]
	v_pk_fma_f32 v[48:49], v[48:49], v[112:113], v[230:231]
	v_mul_f32_e32 v220, v53, v53
	v_mul_f32_e32 v221, v55, v55
	v_fmac_f32_e32 v186, v60, v60
	v_fmac_f32_e32 v187, v62, v62
	v_fmac_f32_e32 v218, v56, v56
	v_fmac_f32_e32 v219, v58, v58
	v_mul_f32_e32 v222, v49, v49
	v_mul_f32_e32 v223, v51, v51
	v_fmac_f32_e32 v220, v52, v52
	v_fmac_f32_e32 v221, v54, v54
	v_add_f32_e32 v186, v186, v187
	v_add_f32_e32 v187, v218, v219
	v_fmac_f32_e32 v222, v48, v48
	v_fmac_f32_e32 v223, v50, v50
	v_add_f32_e32 v218, v220, v221
	v_add_f32_e32 v186, v186, v187
	v_add_f32_e32 v186, v186, v218
	v_add_f32_e32 v187, v222, v223
	v_add_f32_e32 v186, v187, v186
	v_mov_b32_e32 v187, v186
	s_nop 1
	v_permlane16_swap_b32_e32 v186, v187
	s_nop 1
	s_waitcnt lgkmcnt(0)
	v_add_f32_e32 v186, v186, v187
	v_mov_b32_e32 v187, v186
	s_nop 1
	v_permlane32_swap_b32_e32 v186, v187
	s_nop 1
	s_and_saveexec_b64 s[72:73], s[4:5]
	s_cbranch_execz .LBB0_1799
	s_waitcnt lgkmcnt(0)
	v_add_f32_e32 v186, v186, v187
	ds_write_b32 v215, v186 offset:2048
.LBB0_1799:
	s_or_b64 exec, exec, s[72:73]
	s_waitcnt vmcnt(1)
	v_lshlrev_b32_e32 v186, 16, v68
	s_waitcnt lgkmcnt(0)
	v_and_b32_e32 v187, 0xffff0000, v68
	v_lshlrev_b32_e32 v68, 16, v69
	v_and_b32_e32 v69, 0xffff0000, v69
	v_lshlrev_b32_e32 v218, 16, v70
	v_and_b32_e32 v219, 0xffff0000, v70
	v_lshlrev_b32_e32 v70, 16, v71
	v_and_b32_e32 v71, 0xffff0000, v71
	s_waitcnt vmcnt(0)
	v_lshlrev_b32_e32 v220, 16, v64
	v_and_b32_e32 v221, 0xffff0000, v64
	v_lshlrev_b32_e32 v222, 16, v65
	v_and_b32_e32 v223, 0xffff0000, v65
	v_lshlrev_b32_e32 v224, 16, v66
	v_and_b32_e32 v225, 0xffff0000, v66
	v_lshlrev_b32_e32 v226, 16, v67
	v_and_b32_e32 v227, 0xffff0000, v67
	v_pk_fma_f32 v[64:65], v[46:47], v[134:135], v[68:69]
	v_pk_fma_f32 v[66:67], v[44:45], v[132:133], v[186:187]
	v_pk_fma_f32 v[68:69], v[42:43], v[130:131], v[70:71]
	v_pk_fma_f32 v[70:71], v[40:41], v[128:129], v[218:219]
	v_mul_f32_e32 v44, v67, v67
	v_mul_f32_e32 v45, v65, v65
	v_mul_f32_e32 v40, v71, v71
	v_mul_f32_e32 v41, v69, v69
	v_fmac_f32_e32 v44, v66, v66
	v_fmac_f32_e32 v45, v64, v64
	v_fmac_f32_e32 v40, v70, v70
	v_fmac_f32_e32 v41, v68, v68
	v_add_f32_e32 v44, v44, v45
	v_add_f32_e32 v40, v40, v41
	v_add_f32_e32 v44, v44, v40
	v_pk_fma_f32 v[40:41], v[38:39], v[122:123], v[222:223]
	v_pk_fma_f32 v[42:43], v[36:37], v[120:121], v[220:221]
	v_mul_f32_e32 v37, v41, v41
	v_mul_f32_e32 v36, v43, v43
	v_fmac_f32_e32 v36, v42, v42
	v_fmac_f32_e32 v37, v40, v40
	v_add_f32_e32 v36, v36, v37
	v_add_f32_e32 v36, v44, v36
	v_pk_fma_f32 v[44:45], v[34:35], v[114:115], v[226:227]
	v_pk_fma_f32 v[46:47], v[32:33], v[112:113], v[224:225]
	v_mul_f32_e32 v33, v45, v45
	v_mul_f32_e32 v32, v47, v47
	v_fmac_f32_e32 v32, v46, v46
	v_fmac_f32_e32 v33, v44, v44
	v_add_f32_e32 v32, v32, v33
	v_add_f32_e32 v32, v32, v36
	v_mov_b32_e32 v33, v32
	s_nop 1
	v_permlane16_swap_b32_e32 v32, v33
	s_nop 1
	s_waitcnt lgkmcnt(0)
	v_add_f32_e32 v32, v32, v33
	v_mov_b32_e32 v33, v32
	s_nop 1
	v_permlane32_swap_b32_e32 v32, v33
	s_nop 1
	s_and_saveexec_b64 s[72:73], s[4:5]
	s_cbranch_execz .LBB0_1801
	s_waitcnt lgkmcnt(0)
	v_add_f32_e32 v32, v32, v33
	ds_write_b32 v215, v32 offset:2304
.LBB0_1801:
	s_or_b64 exec, exec, s[72:73]
	s_waitcnt lgkmcnt(0)
	v_lshlrev_b64 v[32:33], 11, v[178:179]
	s_mov_b64 s[58:59], 0x50000
	v_lshl_add_u64 v[186:187], v[32:33], 0, s[58:59]
	v_lshl_add_u64 v[34:35], v[180:181], 0, v[186:187]
	global_load_dwordx4 v[218:221], v[34:35], off
	global_load_dwordx4 v[222:225], v[34:35], off offset:256
	s_mov_b64 s[58:59], 0x58000
	v_lshl_add_u64 v[178:179], v[32:33], 0, s[58:59]
	v_lshl_add_u64 v[32:33], v[180:181], 0, v[178:179]
	global_load_dwordx4 v[36:39], v[32:33], off
	s_nop 0
	global_load_dwordx4 v[32:35], v[32:33], off offset:256
	s_waitcnt vmcnt(3)
	v_lshlrev_b32_e32 v180, 16, v218
	v_and_b32_e32 v181, 0xffff0000, v218
	v_lshlrev_b32_e32 v218, 16, v219
	v_and_b32_e32 v219, 0xffff0000, v219
	v_lshlrev_b32_e32 v226, 16, v220
	v_and_b32_e32 v227, 0xffff0000, v220
	v_lshlrev_b32_e32 v220, 16, v221
	v_and_b32_e32 v221, 0xffff0000, v221
	s_waitcnt vmcnt(2)
	v_lshlrev_b32_e32 v228, 16, v222
	v_and_b32_e32 v229, 0xffff0000, v222
	v_lshlrev_b32_e32 v222, 16, v223
	v_and_b32_e32 v223, 0xffff0000, v223
	v_pk_fma_f32 v[30:31], v[30:31], v[134:135], v[218:219]
	v_pk_fma_f32 v[28:29], v[28:29], v[132:133], v[180:181]
	v_pk_fma_f32 v[26:27], v[26:27], v[130:131], v[220:221]
	v_pk_fma_f32 v[24:25], v[24:25], v[128:129], v[226:227]
	v_lshlrev_b32_e32 v230, 16, v224
	v_and_b32_e32 v231, 0xffff0000, v224
	v_lshlrev_b32_e32 v224, 16, v225
	v_and_b32_e32 v225, 0xffff0000, v225
	v_pk_fma_f32 v[22:23], v[22:23], v[122:123], v[222:223]
	v_pk_fma_f32 v[20:21], v[20:21], v[120:121], v[228:229]
	v_mul_f32_e32 v180, v29, v29
	v_mul_f32_e32 v181, v31, v31
	v_mul_f32_e32 v218, v25, v25
	v_mul_f32_e32 v219, v27, v27
	v_pk_fma_f32 v[18:19], v[18:19], v[114:115], v[224:225]
	v_pk_fma_f32 v[16:17], v[16:17], v[112:113], v[230:231]
	v_mul_f32_e32 v220, v21, v21
	v_mul_f32_e32 v221, v23, v23
	v_fmac_f32_e32 v180, v28, v28
	v_fmac_f32_e32 v181, v30, v30
	v_fmac_f32_e32 v218, v24, v24
	v_fmac_f32_e32 v219, v26, v26
	v_mul_f32_e32 v222, v17, v17
	v_mul_f32_e32 v223, v19, v19
	v_fmac_f32_e32 v220, v20, v20
	v_fmac_f32_e32 v221, v22, v22
	v_add_f32_e32 v180, v180, v181
	v_add_f32_e32 v181, v218, v219
	v_fmac_f32_e32 v222, v16, v16
	v_fmac_f32_e32 v223, v18, v18
	v_add_f32_e32 v218, v220, v221
	v_add_f32_e32 v180, v180, v181
	v_add_f32_e32 v180, v180, v218
	v_add_f32_e32 v181, v222, v223
	v_add_f32_e32 v180, v181, v180
	v_mov_b32_e32 v181, v180
	s_nop 1
	v_permlane16_swap_b32_e32 v180, v181
	s_nop 1
	s_waitcnt lgkmcnt(0)
	v_add_f32_e32 v180, v180, v181
	v_mov_b32_e32 v181, v180
	s_nop 1
	v_permlane32_swap_b32_e32 v180, v181
	s_nop 1
	s_and_saveexec_b64 s[72:73], s[4:5]
	s_cbranch_execz .LBB0_1803
	s_waitcnt lgkmcnt(0)
	v_add_f32_e32 v180, v180, v181
	ds_write_b32 v215, v180 offset:2560
.LBB0_1803:
	s_or_b64 exec, exec, s[72:73]
	s_waitcnt vmcnt(1)
	v_lshlrev_b32_e32 v180, 16, v36
	s_waitcnt lgkmcnt(0)
	v_and_b32_e32 v181, 0xffff0000, v36
	v_lshlrev_b32_e32 v36, 16, v37
	v_and_b32_e32 v37, 0xffff0000, v37
	v_lshlrev_b32_e32 v218, 16, v38
	v_and_b32_e32 v219, 0xffff0000, v38
	v_lshlrev_b32_e32 v38, 16, v39
	v_and_b32_e32 v39, 0xffff0000, v39
	s_waitcnt vmcnt(0)
	v_lshlrev_b32_e32 v220, 16, v32
	v_and_b32_e32 v221, 0xffff0000, v32
	v_lshlrev_b32_e32 v222, 16, v33
	v_and_b32_e32 v223, 0xffff0000, v33
	v_lshlrev_b32_e32 v224, 16, v34
	v_and_b32_e32 v225, 0xffff0000, v34
	v_lshlrev_b32_e32 v226, 16, v35
	v_and_b32_e32 v227, 0xffff0000, v35
	v_pk_fma_f32 v[32:33], v[14:15], v[134:135], v[36:37]
	v_pk_fma_f32 v[34:35], v[12:13], v[132:133], v[180:181]
	v_pk_fma_f32 v[36:37], v[10:11], v[130:131], v[38:39]
	v_pk_fma_f32 v[38:39], v[8:9], v[128:129], v[218:219]
	v_mul_f32_e32 v12, v35, v35
	v_mul_f32_e32 v13, v33, v33
	v_mul_f32_e32 v8, v39, v39
	v_mul_f32_e32 v9, v37, v37
	v_fmac_f32_e32 v12, v34, v34
	v_fmac_f32_e32 v13, v32, v32
	v_fmac_f32_e32 v8, v38, v38
	v_fmac_f32_e32 v9, v36, v36
	v_add_f32_e32 v12, v12, v13
	v_add_f32_e32 v8, v8, v9
	v_add_f32_e32 v12, v12, v8
	v_pk_fma_f32 v[8:9], v[6:7], v[122:123], v[222:223]
	v_pk_fma_f32 v[10:11], v[4:5], v[120:121], v[220:221]
	v_mul_f32_e32 v5, v9, v9
	v_mul_f32_e32 v4, v11, v11
	v_fmac_f32_e32 v4, v10, v10
	v_fmac_f32_e32 v5, v8, v8
	v_add_f32_e32 v4, v4, v5
	v_add_f32_e32 v4, v12, v4
	v_pk_fma_f32 v[12:13], v[2:3], v[114:115], v[226:227]
	v_pk_fma_f32 v[14:15], v[0:1], v[112:113], v[224:225]
	v_mul_f32_e32 v1, v13, v13
	v_mul_f32_e32 v0, v15, v15
	v_fmac_f32_e32 v0, v14, v14
	v_fmac_f32_e32 v1, v12, v12
	v_add_f32_e32 v0, v0, v1
	v_add_f32_e32 v0, v0, v4
	v_mov_b32_e32 v1, v0
	s_nop 1
	v_permlane16_swap_b32_e32 v0, v1
	s_nop 1
	s_waitcnt lgkmcnt(0)
	v_add_f32_e32 v0, v0, v1
	v_mov_b32_e32 v1, v0
	s_nop 1
	v_permlane32_swap_b32_e32 v0, v1
	s_nop 1
	s_and_saveexec_b64 s[72:73], s[4:5]
	s_cbranch_execz .LBB0_1805
	s_waitcnt lgkmcnt(0)
	v_add_f32_e32 v0, v0, v1
	ds_write_b32 v215, v0 offset:2816

.LBB0_1952:
	s_lshl_b32 s41, s10, 8
	s_add_i32 s11, s41, 0xfffff000
	v_lshl_add_u32 v168, s50, 8, v176
	v_add_u32_e32 v170, s41, v174
	s_lshr_b32 s11, s11, 11
	v_ashrrev_i32_e32 v169, 31, v168
	v_ashrrev_i32_e32 v171, 31, v170
	s_mulk_i32 s11, 0x1800
	s_cmp_gt_i32 s10, 15
	v_lshl_add_u64 v[172:173], v[168:169], 1, s[20:21]
	v_lshlrev_b64 v[112:113], 11, v[170:171]
	s_cselect_b32 s16, s11, 0x6000
	v_lshl_add_u64 v[112:113], v[172:173], 0, v[112:113]
	s_lshl_b64 s[54:55], s[16:17], 2
	global_load_dwordx4 v[204:207], v[112:113], off
	global_load_dwordx4 v[208:211], v[112:113], off offset:256
	s_add_u32 s54, s64, s54
	s_addc_u32 s55, s65, s55
	v_lshl_add_u64 v[112:113], v[168:169], 2, s[54:55]
	global_load_dwordx4 v[132:135], v[112:113], off
	global_load_dwordx4 v[124:127], v[112:113], off offset:16
	global_load_dwordx4 v[116:119], v[112:113], off offset:512
	s_nop 0
	global_load_dwordx4 v[112:115], v[112:113], off offset:528
	v_or_b32_e32 v144, 16, v170
	v_ashrrev_i32_e32 v145, 31, v144
	v_lshlrev_b64 v[144:145], 11, v[144:145]
	v_lshl_add_u64 v[144:145], v[172:173], 0, v[144:145]
	global_load_dwordx4 v[148:151], v[144:145], off
	s_nop 0
	global_load_dwordx4 v[144:147], v[144:145], off offset:256
	v_and_b32_e32 v203, 64, v197
	v_xor_b32_e32 v202, 16, v197
	v_add_u32_e32 v203, 64, v203
	v_cmp_lt_i32_e32 vcc, v202, v203
	s_waitcnt vmcnt(0)
	v_lshlrev_b32_e32 v212, 16, v204
	v_and_b32_e32 v213, 0xffff0000, v204
	v_lshlrev_b32_e32 v204, 16, v205
	v_and_b32_e32 v205, 0xffff0000, v205
	v_lshlrev_b32_e32 v214, 16, v206
	v_and_b32_e32 v215, 0xffff0000, v206
	v_lshlrev_b32_e32 v206, 16, v207
	v_and_b32_e32 v207, 0xffff0000, v207
	v_lshlrev_b32_e32 v216, 16, v208
	v_and_b32_e32 v217, 0xffff0000, v208
	v_lshlrev_b32_e32 v208, 16, v209
	v_and_b32_e32 v209, 0xffff0000, v209
	v_pk_fma_f32 v[142:143], v[142:143], v[134:135], v[204:205]
	v_pk_fma_f32 v[140:141], v[140:141], v[132:133], v[212:213]
	v_pk_fma_f32 v[138:139], v[138:139], v[126:127], v[206:207]
	v_pk_fma_f32 v[136:137], v[136:137], v[124:125], v[214:215]
	v_lshlrev_b32_e32 v218, 16, v210
	v_and_b32_e32 v219, 0xffff0000, v210
	v_lshlrev_b32_e32 v210, 16, v211
	v_and_b32_e32 v211, 0xffff0000, v211
	v_pk_fma_f32 v[130:131], v[130:131], v[118:119], v[208:209]
	v_pk_fma_f32 v[128:129], v[128:129], v[116:117], v[216:217]
	v_mul_f32_e32 v204, v141, v141
	v_mul_f32_e32 v205, v143, v143
	v_mul_f32_e32 v206, v137, v137
	v_mul_f32_e32 v207, v139, v139
	v_pk_fma_f32 v[122:123], v[122:123], v[114:115], v[210:211]
	v_pk_fma_f32 v[120:121], v[120:121], v[112:113], v[218:219]
	v_mul_f32_e32 v208, v129, v129
	v_mul_f32_e32 v209, v131, v131
	v_fmac_f32_e32 v204, v140, v140
	v_fmac_f32_e32 v205, v142, v142
	v_fmac_f32_e32 v206, v136, v136
	v_fmac_f32_e32 v207, v138, v138
	v_mul_f32_e32 v210, v121, v121
	v_mul_f32_e32 v211, v123, v123
	v_fmac_f32_e32 v208, v128, v128
	v_fmac_f32_e32 v209, v130, v130
	v_add_f32_e32 v204, v204, v205
	v_add_f32_e32 v205, v206, v207
	v_fmac_f32_e32 v210, v120, v120
	v_fmac_f32_e32 v211, v122, v122
	v_add_f32_e32 v206, v208, v209
	v_add_f32_e32 v204, v204, v205
	v_cndmask_b32_e32 v202, v197, v202, vcc
	v_add_f32_e32 v204, v204, v206
	v_add_f32_e32 v205, v210, v211
	v_lshlrev_b32_e32 v202, 2, v202
	v_add_f32_e32 v204, v205, v204
	v_mov_b32_e32 v205, v204
	s_nop 1
	v_permlane16_swap_b32_e32 v204, v205
	s_nop 1
	v_xor_b32_e32 v206, 32, v197
	v_cmp_lt_i32_e32 vcc, v206, v203
	s_waitcnt lgkmcnt(0)
	v_add_f32_e32 v204, v204, v205
	v_cndmask_b32_e32 v203, v197, v206, vcc
	v_lshlrev_b32_e32 v203, 2, v203
	v_mov_b32_e32 v205, v204
	s_nop 1
	v_permlane32_swap_b32_e32 v204, v205
	s_nop 1
	s_and_saveexec_b64 s[54:55], s[0:1]
	s_cbranch_execz .LBB0_1954
	s_waitcnt lgkmcnt(0)
	v_add_f32_e32 v204, v204, v205
	ds_write_b32 v201, v204
.LBB0_1954:
	s_or_b64 exec, exec, s[54:55]
	v_lshlrev_b32_e32 v204, 16, v148
	s_waitcnt lgkmcnt(0)
	v_and_b32_e32 v205, 0xffff0000, v148
	v_lshlrev_b32_e32 v148, 16, v149
	v_and_b32_e32 v149, 0xffff0000, v149
	v_lshlrev_b32_e32 v206, 16, v150
	v_and_b32_e32 v207, 0xffff0000, v150
	v_lshlrev_b32_e32 v150, 16, v151
	v_and_b32_e32 v151, 0xffff0000, v151
	v_lshlrev_b32_e32 v208, 16, v144
	v_and_b32_e32 v209, 0xffff0000, v144
	v_lshlrev_b32_e32 v210, 16, v145
	v_and_b32_e32 v211, 0xffff0000, v145
	v_lshlrev_b32_e32 v212, 16, v146
	v_and_b32_e32 v213, 0xffff0000, v146
	v_lshlrev_b32_e32 v214, 16, v147
	v_and_b32_e32 v215, 0xffff0000, v147
	v_pk_fma_f32 v[144:145], v[110:111], v[134:135], v[148:149]
	v_pk_fma_f32 v[146:147], v[108:109], v[132:133], v[204:205]
	v_pk_fma_f32 v[148:149], v[106:107], v[126:127], v[150:151]
	v_pk_fma_f32 v[150:151], v[104:105], v[124:125], v[206:207]
	v_mul_f32_e32 v108, v147, v147
	v_mul_f32_e32 v109, v145, v145
	v_mul_f32_e32 v104, v151, v151
	v_mul_f32_e32 v105, v149, v149
	v_fmac_f32_e32 v108, v146, v146
	v_fmac_f32_e32 v109, v144, v144
	v_fmac_f32_e32 v104, v150, v150
	v_fmac_f32_e32 v105, v148, v148
	v_add_f32_e32 v108, v108, v109
	v_add_f32_e32 v104, v104, v105
	v_add_f32_e32 v108, v108, v104
	v_pk_fma_f32 v[104:105], v[102:103], v[118:119], v[210:211]
	v_pk_fma_f32 v[106:107], v[100:101], v[116:117], v[208:209]
	v_mul_f32_e32 v101, v105, v105
	v_mul_f32_e32 v100, v107, v107
	v_fmac_f32_e32 v100, v106, v106
	v_fmac_f32_e32 v101, v104, v104
	v_add_f32_e32 v100, v100, v101
	v_add_f32_e32 v100, v108, v100
	v_pk_fma_f32 v[108:109], v[98:99], v[114:115], v[214:215]
	v_pk_fma_f32 v[110:111], v[96:97], v[112:113], v[212:213]
	v_mul_f32_e32 v97, v109, v109
	v_mul_f32_e32 v96, v111, v111
	v_fmac_f32_e32 v96, v110, v110
	v_fmac_f32_e32 v97, v108, v108
	v_add_f32_e32 v96, v96, v97
	v_add_f32_e32 v96, v96, v100
	v_mov_b32_e32 v97, v96
	s_nop 1
	v_permlane16_swap_b32_e32 v96, v97
	s_nop 1
	s_waitcnt lgkmcnt(0)
	v_add_f32_e32 v96, v96, v97
	v_mov_b32_e32 v97, v96
	s_nop 1
	v_permlane32_swap_b32_e32 v96, v97
	s_nop 1
	s_and_saveexec_b64 s[54:55], s[0:1]
	s_cbranch_execz .LBB0_1956
	s_waitcnt lgkmcnt(0)
	v_add_f32_e32 v96, v96, v97
	ds_write_b32 v201, v96 offset:256
.LBB0_1956:
	s_or_b64 exec, exec, s[54:55]
	v_or_b32_e32 v96, 32, v170
	s_waitcnt lgkmcnt(0)
	v_ashrrev_i32_e32 v97, 31, v96
	v_lshlrev_b64 v[96:97], 11, v[96:97]
	v_lshl_add_u64 v[96:97], v[172:173], 0, v[96:97]
	global_load_dwordx4 v[204:207], v[96:97], off
	global_load_dwordx4 v[208:211], v[96:97], off offset:256
	v_or_b32_e32 v96, 48, v170
	v_ashrrev_i32_e32 v97, 31, v96
	v_lshlrev_b64 v[96:97], 11, v[96:97]
	v_lshl_add_u64 v[96:97], v[172:173], 0, v[96:97]
	global_load_dwordx4 v[100:103], v[96:97], off
	s_nop 0
	global_load_dwordx4 v[96:99], v[96:97], off offset:256
	s_waitcnt vmcnt(3)
	v_lshlrev_b32_e32 v212, 16, v204
	v_and_b32_e32 v213, 0xffff0000, v204
	v_lshlrev_b32_e32 v204, 16, v205
	v_and_b32_e32 v205, 0xffff0000, v205
	v_lshlrev_b32_e32 v214, 16, v206
	v_and_b32_e32 v215, 0xffff0000, v206
	v_lshlrev_b32_e32 v206, 16, v207
	v_and_b32_e32 v207, 0xffff0000, v207
	s_waitcnt vmcnt(2)
	v_lshlrev_b32_e32 v216, 16, v208
	v_and_b32_e32 v217, 0xffff0000, v208
	v_lshlrev_b32_e32 v208, 16, v209
	v_and_b32_e32 v209, 0xffff0000, v209
	v_pk_fma_f32 v[94:95], v[94:95], v[134:135], v[204:205]
	v_pk_fma_f32 v[92:93], v[92:93], v[132:133], v[212:213]
	v_pk_fma_f32 v[90:91], v[90:91], v[126:127], v[206:207]
	v_pk_fma_f32 v[88:89], v[88:89], v[124:125], v[214:215]
	v_lshlrev_b32_e32 v218, 16, v210
	v_and_b32_e32 v219, 0xffff0000, v210
	v_lshlrev_b32_e32 v210, 16, v211
	v_and_b32_e32 v211, 0xffff0000, v211
	v_pk_fma_f32 v[86:87], v[86:87], v[118:119], v[208:209]
	v_pk_fma_f32 v[84:85], v[84:85], v[116:117], v[216:217]
	v_mul_f32_e32 v204, v93, v93
	v_mul_f32_e32 v205, v95, v95
	v_mul_f32_e32 v206, v89, v89
	v_mul_f32_e32 v207, v91, v91
	v_pk_fma_f32 v[82:83], v[82:83], v[114:115], v[210:211]
	v_pk_fma_f32 v[80:81], v[80:81], v[112:113], v[218:219]
	v_mul_f32_e32 v208, v85, v85
	v_mul_f32_e32 v209, v87, v87
	v_fmac_f32_e32 v204, v92, v92
	v_fmac_f32_e32 v205, v94, v94
	v_fmac_f32_e32 v206, v88, v88
	v_fmac_f32_e32 v207, v90, v90
	v_mul_f32_e32 v210, v81, v81
	v_mul_f32_e32 v211, v83, v83
	v_fmac_f32_e32 v208, v84, v84
	v_fmac_f32_e32 v209, v86, v86
	v_add_f32_e32 v204, v204, v205
	v_add_f32_e32 v205, v206, v207
	v_fmac_f32_e32 v210, v80, v80
	v_fmac_f32_e32 v211, v82, v82
	v_add_f32_e32 v206, v208, v209
	v_add_f32_e32 v204, v204, v205
	v_add_f32_e32 v204, v204, v206
	v_add_f32_e32 v205, v210, v211
	v_add_f32_e32 v204, v205, v204
	v_mov_b32_e32 v205, v204
	s_nop 1
	v_permlane16_swap_b32_e32 v204, v205
	s_nop 1
	s_waitcnt lgkmcnt(0)
	v_add_f32_e32 v204, v204, v205
	v_mov_b32_e32 v205, v204
	s_nop 1
	v_permlane32_swap_b32_e32 v204, v205
	s_nop 1
	s_and_saveexec_b64 s[54:55], s[0:1]
	s_cbranch_execz .LBB0_1958
	s_waitcnt lgkmcnt(0)
	v_add_f32_e32 v204, v204, v205
	ds_write_b32 v201, v204 offset:512
.LBB0_1958:
	s_or_b64 exec, exec, s[54:55]
	s_waitcnt vmcnt(1)
	v_lshlrev_b32_e32 v204, 16, v100
	s_waitcnt lgkmcnt(0)
	v_and_b32_e32 v205, 0xffff0000, v100
	v_lshlrev_b32_e32 v100, 16, v101
	v_and_b32_e32 v101, 0xffff0000, v101
	v_lshlrev_b32_e32 v206, 16, v102
	v_and_b32_e32 v207, 0xffff0000, v102
	v_lshlrev_b32_e32 v102, 16, v103
	v_and_b32_e32 v103, 0xffff0000, v103
	s_waitcnt vmcnt(0)
	v_lshlrev_b32_e32 v208, 16, v96
	v_and_b32_e32 v209, 0xffff0000, v96
	v_lshlrev_b32_e32 v210, 16, v97
	v_and_b32_e32 v211, 0xffff0000, v97
	v_lshlrev_b32_e32 v212, 16, v98
	v_and_b32_e32 v213, 0xffff0000, v98
	v_lshlrev_b32_e32 v214, 16, v99
	v_and_b32_e32 v215, 0xffff0000, v99
	v_pk_fma_f32 v[96:97], v[78:79], v[134:135], v[100:101]
	v_pk_fma_f32 v[98:99], v[76:77], v[132:133], v[204:205]
	v_pk_fma_f32 v[100:101], v[74:75], v[126:127], v[102:103]
	v_pk_fma_f32 v[102:103], v[72:73], v[124:125], v[206:207]
	v_mul_f32_e32 v76, v99, v99
	v_mul_f32_e32 v77, v97, v97
	v_mul_f32_e32 v72, v103, v103
	v_mul_f32_e32 v73, v101, v101
	v_fmac_f32_e32 v76, v98, v98
	v_fmac_f32_e32 v77, v96, v96
	v_fmac_f32_e32 v72, v102, v102
	v_fmac_f32_e32 v73, v100, v100
	v_add_f32_e32 v76, v76, v77
	v_add_f32_e32 v72, v72, v73
	v_add_f32_e32 v76, v76, v72
	v_pk_fma_f32 v[72:73], v[70:71], v[118:119], v[210:211]
	v_pk_fma_f32 v[74:75], v[68:69], v[116:117], v[208:209]
	v_mul_f32_e32 v69, v73, v73
	v_mul_f32_e32 v68, v75, v75
	v_fmac_f32_e32 v68, v74, v74
	v_fmac_f32_e32 v69, v72, v72
	v_add_f32_e32 v68, v68, v69
	v_add_f32_e32 v68, v76, v68
	v_pk_fma_f32 v[76:77], v[66:67], v[114:115], v[214:215]
	v_pk_fma_f32 v[78:79], v[64:65], v[112:113], v[212:213]
	v_mul_f32_e32 v65, v77, v77
	v_mul_f32_e32 v64, v79, v79
	v_fmac_f32_e32 v64, v78, v78
	v_fmac_f32_e32 v65, v76, v76
	v_add_f32_e32 v64, v64, v65
	v_add_f32_e32 v64, v64, v68
	v_mov_b32_e32 v65, v64
	s_nop 1
	v_permlane16_swap_b32_e32 v64, v65
	s_nop 1
	s_waitcnt lgkmcnt(0)
	v_add_f32_e32 v64, v64, v65
	v_mov_b32_e32 v65, v64
	s_nop 1
	v_permlane32_swap_b32_e32 v64, v65
	s_nop 1
	s_and_saveexec_b64 s[54:55], s[0:1]
	s_cbranch_execz .LBB0_1960
	s_waitcnt lgkmcnt(0)
	v_add_f32_e32 v64, v64, v65
	ds_write_b32 v201, v64 offset:768
.LBB0_1960:
	s_or_b64 exec, exec, s[54:55]
	s_waitcnt lgkmcnt(0)
	v_lshlrev_b64 v[64:65], 11, v[170:171]
	v_lshl_add_u64 v[64:65], v[172:173], 0, v[64:65]
	v_add_co_u32_e32 v66, vcc, 0x40000, v64
	s_nop 1
	v_addc_co_u32_e32 v67, vcc, 0, v65, vcc
	global_load_dwordx4 v[204:207], v[66:67], off
	v_lshl_add_u64 v[66:67], v[64:65], 0, s[30:31]
	global_load_dwordx4 v[208:211], v[66:67], off offset:256
	v_lshl_add_u64 v[66:67], v[64:65], 0, s[34:35]
	v_add_co_u32_e32 v64, vcc, 0x48000, v64
	s_waitcnt vmcnt(1)
	v_lshlrev_b32_e32 v212, 16, v204
	v_addc_co_u32_e32 v65, vcc, 0, v65, vcc
	global_load_dwordx4 v[68:71], v[64:65], off
	s_nop 0
	global_load_dwordx4 v[64:67], v[66:67], off offset:256
	v_and_b32_e32 v213, 0xffff0000, v204
	v_lshlrev_b32_e32 v204, 16, v205
	v_and_b32_e32 v205, 0xffff0000, v205
	v_lshlrev_b32_e32 v214, 16, v206
	v_and_b32_e32 v215, 0xffff0000, v206
	v_lshlrev_b32_e32 v206, 16, v207
	v_and_b32_e32 v207, 0xffff0000, v207
	s_waitcnt vmcnt(2)
	v_lshlrev_b32_e32 v216, 16, v208
	v_and_b32_e32 v217, 0xffff0000, v208
	v_lshlrev_b32_e32 v208, 16, v209
	v_and_b32_e32 v209, 0xffff0000, v209
	v_pk_fma_f32 v[62:63], v[62:63], v[134:135], v[204:205]
	v_pk_fma_f32 v[60:61], v[60:61], v[132:133], v[212:213]
	v_pk_fma_f32 v[58:59], v[58:59], v[126:127], v[206:207]
	v_pk_fma_f32 v[56:57], v[56:57], v[124:125], v[214:215]
	v_lshlrev_b32_e32 v218, 16, v210
	v_and_b32_e32 v219, 0xffff0000, v210
	v_lshlrev_b32_e32 v210, 16, v211
	v_and_b32_e32 v211, 0xffff0000, v211
	v_pk_fma_f32 v[54:55], v[54:55], v[118:119], v[208:209]
	v_pk_fma_f32 v[52:53], v[52:53], v[116:117], v[216:217]
	v_mul_f32_e32 v204, v61, v61
	v_mul_f32_e32 v205, v63, v63
	v_mul_f32_e32 v206, v57, v57
	v_mul_f32_e32 v207, v59, v59
	v_pk_fma_f32 v[50:51], v[50:51], v[114:115], v[210:211]
	v_pk_fma_f32 v[48:49], v[48:49], v[112:113], v[218:219]
	v_mul_f32_e32 v208, v53, v53
	v_mul_f32_e32 v209, v55, v55
	v_fmac_f32_e32 v204, v60, v60
	v_fmac_f32_e32 v205, v62, v62
	v_fmac_f32_e32 v206, v56, v56
	v_fmac_f32_e32 v207, v58, v58
	v_mul_f32_e32 v210, v49, v49
	v_mul_f32_e32 v211, v51, v51
	v_fmac_f32_e32 v208, v52, v52
	v_fmac_f32_e32 v209, v54, v54
	v_add_f32_e32 v204, v204, v205
	v_add_f32_e32 v205, v206, v207
	v_fmac_f32_e32 v210, v48, v48
	v_fmac_f32_e32 v211, v50, v50
	v_add_f32_e32 v206, v208, v209
	v_add_f32_e32 v204, v204, v205
	v_add_f32_e32 v204, v204, v206
	v_add_f32_e32 v205, v210, v211
	v_add_f32_e32 v204, v205, v204
	v_mov_b32_e32 v205, v204
	s_nop 1
	v_permlane16_swap_b32_e32 v204, v205
	s_nop 1
	s_waitcnt lgkmcnt(0)
	v_add_f32_e32 v204, v204, v205
	v_mov_b32_e32 v205, v204
	s_nop 1
	v_permlane32_swap_b32_e32 v204, v205
	s_nop 1
	s_and_saveexec_b64 s[54:55], s[0:1]
	s_cbranch_execz .LBB0_1962
	s_waitcnt lgkmcnt(0)
	v_add_f32_e32 v204, v204, v205
	ds_write_b32 v201, v204 offset:2048
.LBB0_1962:
	s_or_b64 exec, exec, s[54:55]
	s_waitcnt vmcnt(1)
	v_lshlrev_b32_e32 v204, 16, v68
	s_waitcnt lgkmcnt(0)
	v_and_b32_e32 v205, 0xffff0000, v68
	v_lshlrev_b32_e32 v68, 16, v69
	v_and_b32_e32 v69, 0xffff0000, v69
	v_lshlrev_b32_e32 v206, 16, v70
	v_and_b32_e32 v207, 0xffff0000, v70
	v_lshlrev_b32_e32 v70, 16, v71
	v_and_b32_e32 v71, 0xffff0000, v71
	s_waitcnt vmcnt(0)
	v_lshlrev_b32_e32 v208, 16, v64
	v_and_b32_e32 v209, 0xffff0000, v64
	v_lshlrev_b32_e32 v210, 16, v65
	v_and_b32_e32 v211, 0xffff0000, v65
	v_lshlrev_b32_e32 v212, 16, v66
	v_and_b32_e32 v213, 0xffff0000, v66
	v_lshlrev_b32_e32 v214, 16, v67
	v_and_b32_e32 v215, 0xffff0000, v67
	v_pk_fma_f32 v[64:65], v[46:47], v[134:135], v[68:69]
	v_pk_fma_f32 v[66:67], v[44:45], v[132:133], v[204:205]
	v_pk_fma_f32 v[68:69], v[42:43], v[126:127], v[70:71]
	v_pk_fma_f32 v[70:71], v[40:41], v[124:125], v[206:207]
	v_mul_f32_e32 v44, v67, v67
	v_mul_f32_e32 v45, v65, v65
	v_mul_f32_e32 v40, v71, v71
	v_mul_f32_e32 v41, v69, v69
	v_fmac_f32_e32 v44, v66, v66
	v_fmac_f32_e32 v45, v64, v64
	v_fmac_f32_e32 v40, v70, v70
	v_fmac_f32_e32 v41, v68, v68
	v_add_f32_e32 v44, v44, v45
	v_add_f32_e32 v40, v40, v41
	v_add_f32_e32 v44, v44, v40
	v_pk_fma_f32 v[40:41], v[38:39], v[118:119], v[210:211]
	v_pk_fma_f32 v[42:43], v[36:37], v[116:117], v[208:209]
	v_mul_f32_e32 v37, v41, v41
	v_mul_f32_e32 v36, v43, v43
	v_fmac_f32_e32 v36, v42, v42
	v_fmac_f32_e32 v37, v40, v40
	v_add_f32_e32 v36, v36, v37
	v_add_f32_e32 v36, v44, v36
	v_pk_fma_f32 v[44:45], v[34:35], v[114:115], v[214:215]
	v_pk_fma_f32 v[46:47], v[32:33], v[112:113], v[212:213]
	v_mul_f32_e32 v33, v45, v45
	v_mul_f32_e32 v32, v47, v47
	v_fmac_f32_e32 v32, v46, v46
	v_fmac_f32_e32 v33, v44, v44
	v_add_f32_e32 v32, v32, v33
	v_add_f32_e32 v32, v32, v36
	v_mov_b32_e32 v33, v32
	s_nop 1
	v_permlane16_swap_b32_e32 v32, v33
	s_nop 1
	s_waitcnt lgkmcnt(0)
	v_add_f32_e32 v32, v32, v33
	v_mov_b32_e32 v33, v32
	s_nop 1
	v_permlane32_swap_b32_e32 v32, v33
	s_nop 1
	s_and_saveexec_b64 s[54:55], s[0:1]
	s_cbranch_execz .LBB0_1964
	s_waitcnt lgkmcnt(0)
	v_add_f32_e32 v32, v32, v33
	ds_write_b32 v201, v32 offset:2304
.LBB0_1964:
	s_or_b64 exec, exec, s[54:55]
	s_waitcnt lgkmcnt(0)
	v_lshlrev_b64 v[32:33], 11, v[170:171]
	v_lshl_add_u64 v[32:33], v[172:173], 0, v[32:33]
	v_add_co_u32_e32 v34, vcc, 0x50000, v32
	s_nop 1
	v_addc_co_u32_e32 v35, vcc, 0, v33, vcc
	global_load_dwordx4 v[204:207], v[34:35], off
	v_lshl_add_u64 v[34:35], v[32:33], 0, s[36:37]
	global_load_dwordx4 v[208:211], v[34:35], off offset:256
	v_lshl_add_u64 v[34:35], v[32:33], 0, s[38:39]
	v_add_co_u32_e32 v32, vcc, 0x58000, v32
	s_waitcnt vmcnt(1)
	v_lshlrev_b32_e32 v172, 16, v204
	v_addc_co_u32_e32 v33, vcc, 0, v33, vcc
	global_load_dwordx4 v[36:39], v[32:33], off
	s_nop 0
	global_load_dwordx4 v[32:35], v[34:35], off offset:256
	v_and_b32_e32 v173, 0xffff0000, v204
	v_lshlrev_b32_e32 v204, 16, v205
	v_and_b32_e32 v205, 0xffff0000, v205
	v_lshlrev_b32_e32 v212, 16, v206
	v_and_b32_e32 v213, 0xffff0000, v206
	v_lshlrev_b32_e32 v206, 16, v207
	v_and_b32_e32 v207, 0xffff0000, v207
	s_waitcnt vmcnt(2)
	v_lshlrev_b32_e32 v214, 16, v208
	v_and_b32_e32 v215, 0xffff0000, v208
	v_lshlrev_b32_e32 v208, 16, v209
	v_and_b32_e32 v209, 0xffff0000, v209
	v_pk_fma_f32 v[30:31], v[30:31], v[134:135], v[204:205]
	v_pk_fma_f32 v[28:29], v[28:29], v[132:133], v[172:173]
	v_pk_fma_f32 v[26:27], v[26:27], v[126:127], v[206:207]
	v_pk_fma_f32 v[24:25], v[24:25], v[124:125], v[212:213]
	v_lshlrev_b32_e32 v216, 16, v210
	v_and_b32_e32 v217, 0xffff0000, v210
	v_lshlrev_b32_e32 v210, 16, v211
	v_and_b32_e32 v211, 0xffff0000, v211
	v_pk_fma_f32 v[22:23], v[22:23], v[118:119], v[208:209]
	v_pk_fma_f32 v[20:21], v[20:21], v[116:117], v[214:215]
	v_mul_f32_e32 v172, v29, v29
	v_mul_f32_e32 v173, v31, v31
	v_mul_f32_e32 v204, v25, v25
	v_mul_f32_e32 v205, v27, v27
	v_pk_fma_f32 v[18:19], v[18:19], v[114:115], v[210:211]
	v_pk_fma_f32 v[16:17], v[16:17], v[112:113], v[216:217]
	v_mul_f32_e32 v206, v21, v21
	v_mul_f32_e32 v207, v23, v23
	v_fmac_f32_e32 v172, v28, v28
	v_fmac_f32_e32 v173, v30, v30
	v_fmac_f32_e32 v204, v24, v24
	v_fmac_f32_e32 v205, v26, v26
	v_mul_f32_e32 v208, v17, v17
	v_mul_f32_e32 v209, v19, v19
	v_fmac_f32_e32 v206, v20, v20
	v_fmac_f32_e32 v207, v22, v22
	v_add_f32_e32 v172, v172, v173
	v_add_f32_e32 v173, v204, v205
	v_fmac_f32_e32 v208, v16, v16
	v_fmac_f32_e32 v209, v18, v18
	v_add_f32_e32 v204, v206, v207
	v_add_f32_e32 v172, v172, v173
	v_add_f32_e32 v172, v172, v204
	v_add_f32_e32 v173, v208, v209
	v_add_f32_e32 v172, v173, v172
	v_mov_b32_e32 v173, v172
	s_nop 1
	v_permlane16_swap_b32_e32 v172, v173
	s_nop 1
	s_waitcnt lgkmcnt(0)
	v_add_f32_e32 v172, v172, v173
	v_mov_b32_e32 v173, v172
	s_nop 1
	v_permlane32_swap_b32_e32 v172, v173
	s_nop 1
	s_and_saveexec_b64 s[54:55], s[0:1]
	s_cbranch_execz .LBB0_1966
	s_waitcnt lgkmcnt(0)
	v_add_f32_e32 v172, v172, v173
	ds_write_b32 v201, v172 offset:2560
.LBB0_1966:
	s_or_b64 exec, exec, s[54:55]
	s_waitcnt vmcnt(1)
	v_lshlrev_b32_e32 v172, 16, v36
	s_waitcnt lgkmcnt(0)
	v_and_b32_e32 v173, 0xffff0000, v36
	v_lshlrev_b32_e32 v36, 16, v37
	v_and_b32_e32 v37, 0xffff0000, v37
	v_lshlrev_b32_e32 v204, 16, v38
	v_and_b32_e32 v205, 0xffff0000, v38
	v_lshlrev_b32_e32 v38, 16, v39
	v_and_b32_e32 v39, 0xffff0000, v39
	s_waitcnt vmcnt(0)
	v_lshlrev_b32_e32 v206, 16, v32
	v_and_b32_e32 v207, 0xffff0000, v32
	v_lshlrev_b32_e32 v208, 16, v33
	v_and_b32_e32 v209, 0xffff0000, v33
	v_lshlrev_b32_e32 v210, 16, v34
	v_and_b32_e32 v211, 0xffff0000, v34
	v_lshlrev_b32_e32 v212, 16, v35
	v_and_b32_e32 v213, 0xffff0000, v35
	v_pk_fma_f32 v[32:33], v[14:15], v[134:135], v[36:37]
	v_pk_fma_f32 v[34:35], v[12:13], v[132:133], v[172:173]
	v_pk_fma_f32 v[36:37], v[10:11], v[126:127], v[38:39]
	v_pk_fma_f32 v[38:39], v[8:9], v[124:125], v[204:205]
	v_mul_f32_e32 v12, v35, v35
	v_mul_f32_e32 v13, v33, v33
	v_mul_f32_e32 v8, v39, v39
	v_mul_f32_e32 v9, v37, v37
	v_fmac_f32_e32 v12, v34, v34
	v_fmac_f32_e32 v13, v32, v32
	v_fmac_f32_e32 v8, v38, v38
	v_fmac_f32_e32 v9, v36, v36
	v_add_f32_e32 v12, v12, v13
	v_add_f32_e32 v8, v8, v9
	v_add_f32_e32 v12, v12, v8
	v_pk_fma_f32 v[8:9], v[6:7], v[118:119], v[208:209]
	v_pk_fma_f32 v[10:11], v[4:5], v[116:117], v[206:207]
	v_mul_f32_e32 v5, v9, v9
	v_mul_f32_e32 v4, v11, v11
	v_fmac_f32_e32 v4, v10, v10
	v_fmac_f32_e32 v5, v8, v8
	v_add_f32_e32 v4, v4, v5
	v_add_f32_e32 v4, v12, v4
	v_pk_fma_f32 v[12:13], v[2:3], v[114:115], v[212:213]
	v_pk_fma_f32 v[14:15], v[0:1], v[112:113], v[210:211]
	v_mul_f32_e32 v1, v13, v13
	v_mul_f32_e32 v0, v15, v15
	v_fmac_f32_e32 v0, v14, v14
	v_fmac_f32_e32 v1, v12, v12
	v_add_f32_e32 v0, v0, v1
	v_add_f32_e32 v0, v0, v4
	v_mov_b32_e32 v1, v0
	s_nop 1
	v_permlane16_swap_b32_e32 v0, v1
	s_nop 1
	s_waitcnt lgkmcnt(0)
	v_add_f32_e32 v0, v0, v1
	v_mov_b32_e32 v1, v0
	s_nop 1
	v_permlane32_swap_b32_e32 v0, v1
	s_nop 1
	s_and_saveexec_b64 s[54:55], s[0:1]
	s_cbranch_execz .LBB0_1968
	s_waitcnt lgkmcnt(0)
	v_add_f32_e32 v0, v0, v1
	ds_write_b32 v201, v0 offset:2816
